# conv-epilogue-dpp-fused-fmac
# speedup vs baseline: 1.0062x; 1.0062x over previous
; __device__ __forceinline__ float conv1(float cur, float prv, float w0, float w1, float w2, float b) {
;     float r, t1, t2;
;     asm volatile(
;         "s_nop 1\n\t"
;         "v_mov_b32_dpp %1, %4 row_ror:1 row_mask:0xf bank_mask:0xf\n\t"
;         "v_mov_b32_dpp %2, %4 row_ror:2 row_mask:0xf bank_mask:0xf\n\t"
;         "v_fma_f32 %0, %7, %3, %8\n\t"
;         "v_mov_b32_dpp %1, %3 row_shr:1 row_mask:0xf bank_mask:0xf\n\t"
;         "v_mov_b32_dpp %2, %3 row_shr:2 row_mask:0xf bank_mask:0xf\n\t"
;         "v_fmac_f32 %0, %6, %1\n\t"
;         "v_fmac_f32 %0, %5, %2\n\t"
;         : "=&v"(r), "=&v"(t1), "=&v"(t2) : "v"(cur), "v"(prv), "v"(w0), "v"(w1), "v"(w2), "v"(b));
;     return r;
; }
;     __device__ __forceinline__ void operator()(f32x4 (&acc)[2][2][4][2], const Unit& u, int wr, int wc, int fr, int fq, LAS unsigned char* xl) const {
;     ...
;         if (MODE == 1) {
; #pragma unroll
;             for (int ai = 0; ai < 2; ++ai)
; #pragma unroll
;                 for (int m = 0; m < 4; ++m)
; #pragma unroll
;                     for (int n = 0; n < 2; ++n) acc[ai][0][m][n] *= acc[ai][1][m][n];
.LBB0_514:
	v_pk_mul_f32 v[204:205], v[96:97], v[80:81]
	v_pk_mul_f32 v[94:95], v[94:95], v[78:79]
	v_pk_mul_f32 v[72:73], v[84:85], v[72:73]
	v_pk_mul_f32 v[74:75], v[86:87], v[74:75]
	s_waitcnt lgkmcnt(0)
	v_fma_f32 v78, v148, v158, v152
	v_fma_f32 v79, v149, v159, v153
	v_fma_f32 v80, v150, v160, v154
	v_fma_f32 v81, v151, v161, v155
	v_fmac_f32_dpp v78, v158, v144 row_shr:1 row_mask:0xf bank_mask:0xf
	v_fmac_f32_dpp v79, v159, v145 row_shr:1 row_mask:0xf bank_mask:0xf
	v_fmac_f32_dpp v80, v160, v146 row_shr:1 row_mask:0xf bank_mask:0xf
	v_fmac_f32_dpp v81, v161, v147 row_shr:1 row_mask:0xf bank_mask:0xf
	v_fmac_f32_dpp v78, v72, v144 row_shl:15 row_mask:0xf bank_mask:0xf
	v_fmac_f32_dpp v79, v73, v145 row_shl:15 row_mask:0xf bank_mask:0xf
	v_fmac_f32_dpp v80, v74, v146 row_shl:15 row_mask:0xf bank_mask:0xf
	v_fmac_f32_dpp v81, v75, v147 row_shl:15 row_mask:0xf bank_mask:0xf
	v_fmac_f32_dpp v78, v158, v140 row_shr:2 row_mask:0xf bank_mask:0xf
	v_fmac_f32_dpp v79, v159, v141 row_shr:2 row_mask:0xf bank_mask:0xf
	v_fmac_f32_dpp v80, v160, v142 row_shr:2 row_mask:0xf bank_mask:0xf
	v_fmac_f32_dpp v81, v161, v143 row_shr:2 row_mask:0xf bank_mask:0xf
	v_fmac_f32_dpp v78, v72, v140 row_shl:14 row_mask:0xf bank_mask:0xf
	v_fmac_f32_dpp v79, v73, v141 row_shl:14 row_mask:0xf bank_mask:0xf
	v_fmac_f32_dpp v80, v74, v142 row_shl:14 row_mask:0xf bank_mask:0xf
	v_fmac_f32_dpp v81, v75, v143 row_shl:14 row_mask:0xf bank_mask:0xf
	v_pk_mul_f32 v[82:83], v[98:99], v[82:83]
	v_pk_mul_f32 v[76:77], v[92:93], v[76:77]
	s_andn2_b64 vcc, exec, s[64:65]
	v_mov_b32_e32 v157, 0
	v_fma_f32 v85, v148, v72, v152
	v_fma_f32 v87, v149, v73, v153
	v_fma_f32 v92, v150, v74, v154
	v_fma_f32 v93, v151, v75, v155
	v_fmac_f32_dpp v85, v72, v144 row_shr:1 row_mask:0xf bank_mask:0xf
	v_fmac_f32_dpp v87, v73, v145 row_shr:1 row_mask:0xf bank_mask:0xf
	v_fmac_f32_dpp v92, v74, v146 row_shr:1 row_mask:0xf bank_mask:0xf
	v_fmac_f32_dpp v93, v75, v147 row_shr:1 row_mask:0xf bank_mask:0xf
	v_fmac_f32_dpp v85, v76, v144 row_shl:15 row_mask:0xf bank_mask:0xf
	v_fmac_f32_dpp v87, v77, v145 row_shl:15 row_mask:0xf bank_mask:0xf
	v_fmac_f32_dpp v92, v94, v146 row_shl:15 row_mask:0xf bank_mask:0xf
	v_fmac_f32_dpp v93, v95, v147 row_shl:15 row_mask:0xf bank_mask:0xf
	v_fmac_f32_dpp v85, v72, v140 row_shr:2 row_mask:0xf bank_mask:0xf
	v_fmac_f32_dpp v87, v73, v141 row_shr:2 row_mask:0xf bank_mask:0xf
	v_fmac_f32_dpp v92, v74, v142 row_shr:2 row_mask:0xf bank_mask:0xf
	v_fmac_f32_dpp v93, v75, v143 row_shr:2 row_mask:0xf bank_mask:0xf
	v_fmac_f32_dpp v85, v76, v140 row_shl:14 row_mask:0xf bank_mask:0xf
	v_fmac_f32_dpp v87, v77, v141 row_shl:14 row_mask:0xf bank_mask:0xf
	v_fmac_f32_dpp v92, v94, v142 row_shl:14 row_mask:0xf bank_mask:0xf
	v_fmac_f32_dpp v93, v95, v143 row_shl:14 row_mask:0xf bank_mask:0xf
	v_mov_b32_e32 v158, 0
	v_mov_b32_e32 v159, 0
	s_nop 0
	v_fma_f32 v97, v148, v76, v152
	v_fma_f32 v99, v149, v77, v153
	v_fma_f32 v160, v150, v94, v154
	v_fma_f32 v161, v151, v95, v155
	v_fmac_f32_dpp v97, v76, v144 row_shr:1 row_mask:0xf bank_mask:0xf
	v_fmac_f32_dpp v99, v77, v145 row_shr:1 row_mask:0xf bank_mask:0xf
	v_fmac_f32_dpp v160, v94, v146 row_shr:1 row_mask:0xf bank_mask:0xf
	v_fmac_f32_dpp v161, v95, v147 row_shr:1 row_mask:0xf bank_mask:0xf
	v_fmac_f32_dpp v97, v204, v144 row_shl:15 row_mask:0xf bank_mask:0xf
	v_fmac_f32_dpp v99, v205, v145 row_shl:15 row_mask:0xf bank_mask:0xf
	v_fmac_f32_dpp v160, v82, v146 row_shl:15 row_mask:0xf bank_mask:0xf
	v_fmac_f32_dpp v161, v83, v147 row_shl:15 row_mask:0xf bank_mask:0xf
	v_fmac_f32_dpp v97, v76, v140 row_shr:2 row_mask:0xf bank_mask:0xf
	v_fmac_f32_dpp v99, v77, v141 row_shr:2 row_mask:0xf bank_mask:0xf
	v_fmac_f32_dpp v160, v94, v142 row_shr:2 row_mask:0xf bank_mask:0xf
	v_fmac_f32_dpp v161, v95, v143 row_shr:2 row_mask:0xf bank_mask:0xf
	v_fmac_f32_dpp v97, v204, v140 row_shl:14 row_mask:0xf bank_mask:0xf
	v_fmac_f32_dpp v99, v205, v141 row_shl:14 row_mask:0xf bank_mask:0xf
	v_fmac_f32_dpp v160, v82, v142 row_shl:14 row_mask:0xf bank_mask:0xf
	v_fmac_f32_dpp v161, v83, v143 row_shl:14 row_mask:0xf bank_mask:0xf
	s_nop 0
	v_fma_f32 v72, v148, v204, v152
	v_fma_f32 v73, v149, v205, v153
	v_fma_f32 v74, v150, v82, v154
	v_fma_f32 v75, v151, v83, v155
	v_fmac_f32_dpp v72, v204, v144 row_shr:1 row_mask:0xf bank_mask:0xf
	v_fmac_f32_dpp v73, v205, v145 row_shr:1 row_mask:0xf bank_mask:0xf
	v_fmac_f32_dpp v74, v82, v146 row_shr:1 row_mask:0xf bank_mask:0xf
	v_fmac_f32_dpp v75, v83, v147 row_shr:1 row_mask:0xf bank_mask:0xf
	v_fmac_f32_dpp v72, v162, v144 row_shl:15 row_mask:0xf bank_mask:0xf
	v_fmac_f32_dpp v73, v163, v145 row_shl:15 row_mask:0xf bank_mask:0xf
	v_fmac_f32_dpp v74, v164, v146 row_shl:15 row_mask:0xf bank_mask:0xf
	v_fmac_f32_dpp v75, v165, v147 row_shl:15 row_mask:0xf bank_mask:0xf
	v_fmac_f32_dpp v72, v204, v140 row_shr:2 row_mask:0xf bank_mask:0xf
	v_fmac_f32_dpp v73, v205, v141 row_shr:2 row_mask:0xf bank_mask:0xf
	v_fmac_f32_dpp v74, v82, v142 row_shr:2 row_mask:0xf bank_mask:0xf
	v_fmac_f32_dpp v75, v83, v143 row_shr:2 row_mask:0xf bank_mask:0xf
	v_fmac_f32_dpp v72, v162, v140 row_shl:14 row_mask:0xf bank_mask:0xf
	v_fmac_f32_dpp v73, v163, v141 row_shl:14 row_mask:0xf bank_mask:0xf
	v_fmac_f32_dpp v74, v164, v142 row_shl:14 row_mask:0xf bank_mask:0xf
	v_fmac_f32_dpp v75, v165, v143 row_shl:14 row_mask:0xf bank_mask:0xf
	s_nop 0
	v_cndmask_b32_e64 v76, 0, 1, s[64:65]
	v_cmp_ne_u32_e64 s[8:9], 1, v76
	s_cbranch_vccnz .LBB0_516
	ds_read_b128 v[156:159], v188 offset:4096
; #define LAS __attribute__((address_space(3)))
; __device__ __forceinline__ float conv1(float cur, float prv, float w0, float w1, float w2, float b) {
;     float r, t1, t2;
;     asm volatile(
;         "s_nop 1\n\t"
;         "v_mov_b32_dpp %1, %4 row_ror:1 row_mask:0xf bank_mask:0xf\n\t"
;         "v_mov_b32_dpp %2, %4 row_ror:2 row_mask:0xf bank_mask:0xf\n\t"
;         "v_fma_f32 %0, %7, %3, %8\n\t"
;         "v_mov_b32_dpp %1, %3 row_shr:1 row_mask:0xf bank_mask:0xf\n\t"
;         "v_mov_b32_dpp %2, %3 row_shr:2 row_mask:0xf bank_mask:0xf\n\t"
;         "v_fmac_f32 %0, %6, %1\n\t"
;         "v_fmac_f32 %0, %5, %2\n\t"
;         : "=&v"(r), "=&v"(t1), "=&v"(t2) : "v"(cur), "v"(prv), "v"(w0), "v"(w1), "v"(w2), "v"(b));
;     return r;
; }
;     __device__ __forceinline__ void operator()(f32x4 (&acc)[2][2][4][2], const Unit& u, int wr, int wc, int fr, int fq, LAS unsigned char* xl) const {
;     ...
;             for (int n = 0; n < 2; ++n) {
;                 const int lc = s * 128 + chl + 4 * n;
;                 const f32x4 w0 = *(const LAS f32x4*)(wt + lc), w1 = *(const LAS f32x4*)(wt + 256 + lc), w2 = *(const LAS f32x4*)(wt + 512 + lc), bb = *(const LAS f32x4*)(wt + 768 + lc);
; #pragma unroll
;                 for (int ai = 0; ai < 2; ++ai) {
;                     const int blk = ai * 2 + wr;
;                     f32x4 pg = (f32x4){0.f, 0.f, 0.f, 0.f};
;                     if (blk > 0) pg = *(const LAS f32x4*)(bnd + (((blk - 1) * 2 + (fr & 1)) * 256 + lc));
.LBB0_516:
	v_pk_mul_f32 v[58:59], v[70:71], v[58:59]
	v_pk_mul_f32 v[56:57], v[68:69], v[56:57]
	v_pk_mul_f32 v[54:55], v[66:67], v[54:55]
	v_pk_mul_f32 v[52:53], v[64:65], v[52:53]
	v_pk_mul_f32 v[50:51], v[62:63], v[50:51]
	v_pk_mul_f32 v[48:49], v[60:61], v[48:49]
	s_nop 0
	v_fma_f32 v70, v148, v136, v152
	v_fma_f32 v71, v149, v137, v153
	v_fma_f32 v76, v150, v138, v154
	v_fma_f32 v77, v151, v139, v155
	v_fmac_f32_dpp v70, v136, v144 row_shr:1 row_mask:0xf bank_mask:0xf
	v_fmac_f32_dpp v71, v137, v145 row_shr:1 row_mask:0xf bank_mask:0xf
	v_fmac_f32_dpp v76, v138, v146 row_shr:1 row_mask:0xf bank_mask:0xf
	v_fmac_f32_dpp v77, v139, v147 row_shr:1 row_mask:0xf bank_mask:0xf
	v_fmac_f32_dpp v70, v48, v144 row_shl:15 row_mask:0xf bank_mask:0xf
	v_fmac_f32_dpp v71, v49, v145 row_shl:15 row_mask:0xf bank_mask:0xf
	v_fmac_f32_dpp v76, v50, v146 row_shl:15 row_mask:0xf bank_mask:0xf
	v_fmac_f32_dpp v77, v51, v147 row_shl:15 row_mask:0xf bank_mask:0xf
	v_fmac_f32_dpp v70, v136, v140 row_shr:2 row_mask:0xf bank_mask:0xf
	v_fmac_f32_dpp v71, v137, v141 row_shr:2 row_mask:0xf bank_mask:0xf
	v_fmac_f32_dpp v76, v138, v142 row_shr:2 row_mask:0xf bank_mask:0xf
	v_fmac_f32_dpp v77, v139, v143 row_shr:2 row_mask:0xf bank_mask:0xf
	v_fmac_f32_dpp v70, v48, v140 row_shl:14 row_mask:0xf bank_mask:0xf
	v_fmac_f32_dpp v71, v49, v141 row_shl:14 row_mask:0xf bank_mask:0xf
	v_fmac_f32_dpp v76, v50, v142 row_shl:14 row_mask:0xf bank_mask:0xf
	v_fmac_f32_dpp v77, v51, v143 row_shl:14 row_mask:0xf bank_mask:0xf
	s_nop 0
	v_fma_f32 v82, v148, v48, v152
	v_fma_f32 v83, v149, v49, v153
	v_fma_f32 v84, v150, v50, v154
	v_fma_f32 v86, v151, v51, v155
	v_fmac_f32_dpp v82, v48, v144 row_shr:1 row_mask:0xf bank_mask:0xf
	v_fmac_f32_dpp v83, v49, v145 row_shr:1 row_mask:0xf bank_mask:0xf
	v_fmac_f32_dpp v84, v50, v146 row_shr:1 row_mask:0xf bank_mask:0xf
	v_fmac_f32_dpp v86, v51, v147 row_shr:1 row_mask:0xf bank_mask:0xf
	v_fmac_f32_dpp v82, v52, v144 row_shl:15 row_mask:0xf bank_mask:0xf
	v_fmac_f32_dpp v83, v53, v145 row_shl:15 row_mask:0xf bank_mask:0xf
	v_fmac_f32_dpp v84, v54, v146 row_shl:15 row_mask:0xf bank_mask:0xf
	v_fmac_f32_dpp v86, v55, v147 row_shl:15 row_mask:0xf bank_mask:0xf
	v_fmac_f32_dpp v82, v48, v140 row_shr:2 row_mask:0xf bank_mask:0xf
	v_fmac_f32_dpp v83, v49, v141 row_shr:2 row_mask:0xf bank_mask:0xf
	v_fmac_f32_dpp v84, v50, v142 row_shr:2 row_mask:0xf bank_mask:0xf
	v_fmac_f32_dpp v86, v51, v143 row_shr:2 row_mask:0xf bank_mask:0xf
	v_fmac_f32_dpp v82, v52, v140 row_shl:14 row_mask:0xf bank_mask:0xf
	v_fmac_f32_dpp v83, v53, v141 row_shl:14 row_mask:0xf bank_mask:0xf
	v_fmac_f32_dpp v84, v54, v142 row_shl:14 row_mask:0xf bank_mask:0xf
	v_fmac_f32_dpp v86, v55, v143 row_shl:14 row_mask:0xf bank_mask:0xf
	s_nop 0
	v_fma_f32 v94, v148, v52, v152
	v_fma_f32 v95, v149, v53, v153
	v_fma_f32 v96, v150, v54, v154
	v_fma_f32 v98, v151, v55, v155
	v_fmac_f32_dpp v94, v52, v144 row_shr:1 row_mask:0xf bank_mask:0xf
	v_fmac_f32_dpp v95, v53, v145 row_shr:1 row_mask:0xf bank_mask:0xf
	v_fmac_f32_dpp v96, v54, v146 row_shr:1 row_mask:0xf bank_mask:0xf
	v_fmac_f32_dpp v98, v55, v147 row_shr:1 row_mask:0xf bank_mask:0xf
	v_fmac_f32_dpp v94, v56, v144 row_shl:15 row_mask:0xf bank_mask:0xf
	v_fmac_f32_dpp v95, v57, v145 row_shl:15 row_mask:0xf bank_mask:0xf
	v_fmac_f32_dpp v96, v58, v146 row_shl:15 row_mask:0xf bank_mask:0xf
	v_fmac_f32_dpp v98, v59, v147 row_shl:15 row_mask:0xf bank_mask:0xf
	v_fmac_f32_dpp v94, v52, v140 row_shr:2 row_mask:0xf bank_mask:0xf
	v_fmac_f32_dpp v95, v53, v141 row_shr:2 row_mask:0xf bank_mask:0xf
	v_fmac_f32_dpp v96, v54, v142 row_shr:2 row_mask:0xf bank_mask:0xf
	v_fmac_f32_dpp v98, v55, v143 row_shr:2 row_mask:0xf bank_mask:0xf
	v_fmac_f32_dpp v94, v56, v140 row_shl:14 row_mask:0xf bank_mask:0xf
	v_fmac_f32_dpp v95, v57, v141 row_shl:14 row_mask:0xf bank_mask:0xf
	v_fmac_f32_dpp v96, v58, v142 row_shl:14 row_mask:0xf bank_mask:0xf
	v_fmac_f32_dpp v98, v59, v143 row_shl:14 row_mask:0xf bank_mask:0xf
	s_waitcnt lgkmcnt(0)
	v_fma_f32 v136, v148, v56, v152
	v_fma_f32 v137, v149, v57, v153
	v_fma_f32 v138, v150, v58, v154
	v_fma_f32 v139, v151, v59, v155
	v_fmac_f32_dpp v136, v56, v144 row_shr:1 row_mask:0xf bank_mask:0xf
	v_fmac_f32_dpp v137, v57, v145 row_shr:1 row_mask:0xf bank_mask:0xf
	v_fmac_f32_dpp v138, v58, v146 row_shr:1 row_mask:0xf bank_mask:0xf
	v_fmac_f32_dpp v139, v59, v147 row_shr:1 row_mask:0xf bank_mask:0xf
	v_fmac_f32_dpp v136, v156, v144 row_shl:15 row_mask:0xf bank_mask:0xf
	v_fmac_f32_dpp v137, v157, v145 row_shl:15 row_mask:0xf bank_mask:0xf
	v_fmac_f32_dpp v138, v158, v146 row_shl:15 row_mask:0xf bank_mask:0xf
	v_fmac_f32_dpp v139, v159, v147 row_shl:15 row_mask:0xf bank_mask:0xf
	v_fmac_f32_dpp v136, v56, v140 row_shr:2 row_mask:0xf bank_mask:0xf
	v_fmac_f32_dpp v137, v57, v141 row_shr:2 row_mask:0xf bank_mask:0xf
	v_fmac_f32_dpp v138, v58, v142 row_shr:2 row_mask:0xf bank_mask:0xf
	v_fmac_f32_dpp v139, v59, v143 row_shr:2 row_mask:0xf bank_mask:0xf
	v_fmac_f32_dpp v136, v156, v140 row_shl:14 row_mask:0xf bank_mask:0xf
	v_fmac_f32_dpp v137, v157, v141 row_shl:14 row_mask:0xf bank_mask:0xf
	v_fmac_f32_dpp v138, v158, v142 row_shl:14 row_mask:0xf bank_mask:0xf
	v_fmac_f32_dpp v139, v159, v143 row_shl:14 row_mask:0xf bank_mask:0xf
	ds_read_b128 v[48:51], v185
	ds_read_b128 v[52:55], v186
	ds_read_b128 v[56:59], v187
	ds_read_b128 v[60:63], v200
	v_mov_b32_e32 v64, 0
	s_andn2_b64 vcc, exec, s[60:61]
	v_mov_b32_e32 v66, 0
	v_mov_b32_e32 v67, 0
	v_mov_b32_e32 v68, 0
	v_mov_b32_e32 v69, 0
	s_cbranch_vccnz .LBB0_518
	ds_read_b128 v[66:69], v201
; __device__ __forceinline__ float conv1(float cur, float prv, float w0, float w1, float w2, float b) {
;     float r, t1, t2;
;     asm volatile(
;         "s_nop 1\n\t"
;         "v_mov_b32_dpp %1, %4 row_ror:1 row_mask:0xf bank_mask:0xf\n\t"
;         "v_mov_b32_dpp %2, %4 row_ror:2 row_mask:0xf bank_mask:0xf\n\t"
;         "v_fma_f32 %0, %7, %3, %8\n\t"
;         "v_mov_b32_dpp %1, %3 row_shr:1 row_mask:0xf bank_mask:0xf\n\t"
;         "v_mov_b32_dpp %2, %3 row_shr:2 row_mask:0xf bank_mask:0xf\n\t"
;         "v_fmac_f32 %0, %6, %1\n\t"
;         "v_fmac_f32 %0, %5, %2\n\t"
;         : "=&v"(r), "=&v"(t1), "=&v"(t2) : "v"(cur), "v"(prv), "v"(w0), "v"(w1), "v"(w2), "v"(b));
;     return r;
; }
;     __device__ __forceinline__ void operator()(f32x4 (&acc)[2][2][4][2], const Unit& u, int wr, int wc, int fr, int fq, LAS unsigned char* xl) const {
;     ...
;         if (MODE == 1) {
; #pragma unroll
;             for (int ai = 0; ai < 2; ++ai)
; #pragma unroll
;                 for (int m = 0; m < 4; ++m)
; #pragma unroll
;                     for (int n = 0; n < 2; ++n) acc[ai][0][m][n] *= acc[ai][1][m][n];
.LBB0_518:
	v_pk_mul_f32 v[42:43], v[42:43], v[30:31]
	v_pk_mul_f32 v[40:41], v[40:41], v[28:29]
	v_pk_mul_f32 v[24:25], v[36:37], v[24:25]
	v_pk_mul_f32 v[44:45], v[44:45], v[32:33]
	s_waitcnt lgkmcnt(0)
	v_fma_f32 v28, v56, v132, v60
	v_fma_f32 v29, v57, v133, v61
	s_nop 0
	v_fmac_f32_dpp v28, v132, v52 row_shr:1 row_mask:0xf bank_mask:0xf
	v_fmac_f32_dpp v29, v133, v53 row_shr:1 row_mask:0xf bank_mask:0xf
	s_nop 0
	v_fmac_f32_dpp v28, v24, v52 row_shl:15 row_mask:0xf bank_mask:0xf
	v_fmac_f32_dpp v29, v25, v53 row_shl:15 row_mask:0xf bank_mask:0xf
	s_nop 0
	v_fmac_f32_dpp v28, v132, v48 row_shr:2 row_mask:0xf bank_mask:0xf
	v_fmac_f32_dpp v29, v133, v49 row_shr:2 row_mask:0xf bank_mask:0xf
	s_nop 0
	v_fmac_f32_dpp v28, v24, v48 row_shl:14 row_mask:0xf bank_mask:0xf
	v_fmac_f32_dpp v29, v25, v49 row_shl:14 row_mask:0xf bank_mask:0xf
	v_pk_mul_f32 v[26:27], v[38:39], v[26:27]
	v_pk_mul_f32 v[46:47], v[46:47], v[34:35]
	v_fma_f32 v30, v58, v134, v62
	v_fma_f32 v31, v59, v135, v63
	v_fma_f32 v32, v56, v24, v60
	v_fma_f32 v33, v57, v25, v61
	v_fmac_f32_dpp v30, v134, v54 row_shr:1 row_mask:0xf bank_mask:0xf
	v_fmac_f32_dpp v31, v135, v55 row_shr:1 row_mask:0xf bank_mask:0xf
	v_fmac_f32_dpp v32, v24, v52 row_shr:1 row_mask:0xf bank_mask:0xf
	v_fmac_f32_dpp v33, v25, v53 row_shr:1 row_mask:0xf bank_mask:0xf
	v_fmac_f32_dpp v30, v26, v54 row_shl:15 row_mask:0xf bank_mask:0xf
	v_fmac_f32_dpp v31, v27, v55 row_shl:15 row_mask:0xf bank_mask:0xf
	v_fmac_f32_dpp v32, v40, v52 row_shl:15 row_mask:0xf bank_mask:0xf
	v_fmac_f32_dpp v33, v41, v53 row_shl:15 row_mask:0xf bank_mask:0xf
	v_fmac_f32_dpp v30, v134, v50 row_shr:2 row_mask:0xf bank_mask:0xf
	v_fmac_f32_dpp v31, v135, v51 row_shr:2 row_mask:0xf bank_mask:0xf
	v_fmac_f32_dpp v32, v24, v48 row_shr:2 row_mask:0xf bank_mask:0xf
	v_fmac_f32_dpp v33, v25, v49 row_shr:2 row_mask:0xf bank_mask:0xf
	v_fmac_f32_dpp v30, v26, v50 row_shl:14 row_mask:0xf bank_mask:0xf
	v_fmac_f32_dpp v31, v27, v51 row_shl:14 row_mask:0xf bank_mask:0xf
	v_fmac_f32_dpp v32, v40, v48 row_shl:14 row_mask:0xf bank_mask:0xf
	v_fmac_f32_dpp v33, v41, v49 row_shl:14 row_mask:0xf bank_mask:0xf
	s_and_b64 vcc, exec, s[8:9]
	v_mov_b32_e32 v65, 0
	s_nop 0
	v_fma_f32 v34, v58, v26, v62
	v_fma_f32 v35, v59, v27, v63
	v_fma_f32 v36, v56, v40, v60
	v_fma_f32 v37, v57, v41, v61
	v_fmac_f32_dpp v34, v26, v54 row_shr:1 row_mask:0xf bank_mask:0xf
	v_fmac_f32_dpp v35, v27, v55 row_shr:1 row_mask:0xf bank_mask:0xf
	v_fmac_f32_dpp v36, v40, v52 row_shr:1 row_mask:0xf bank_mask:0xf
	v_fmac_f32_dpp v37, v41, v53 row_shr:1 row_mask:0xf bank_mask:0xf
	v_fmac_f32_dpp v34, v42, v54 row_shl:15 row_mask:0xf bank_mask:0xf
	v_fmac_f32_dpp v35, v43, v55 row_shl:15 row_mask:0xf bank_mask:0xf
	v_fmac_f32_dpp v36, v44, v52 row_shl:15 row_mask:0xf bank_mask:0xf
	v_fmac_f32_dpp v37, v45, v53 row_shl:15 row_mask:0xf bank_mask:0xf
	v_fmac_f32_dpp v34, v26, v50 row_shr:2 row_mask:0xf bank_mask:0xf
	v_fmac_f32_dpp v35, v27, v51 row_shr:2 row_mask:0xf bank_mask:0xf
	v_fmac_f32_dpp v36, v40, v48 row_shr:2 row_mask:0xf bank_mask:0xf
	v_fmac_f32_dpp v37, v41, v49 row_shr:2 row_mask:0xf bank_mask:0xf
	v_fmac_f32_dpp v34, v42, v50 row_shl:14 row_mask:0xf bank_mask:0xf
	v_fmac_f32_dpp v35, v43, v51 row_shl:14 row_mask:0xf bank_mask:0xf
	v_fmac_f32_dpp v36, v44, v48 row_shl:14 row_mask:0xf bank_mask:0xf
	v_fmac_f32_dpp v37, v45, v49 row_shl:14 row_mask:0xf bank_mask:0xf
	s_nop 0
	v_fma_f32 v38, v58, v42, v62
	v_fma_f32 v39, v59, v43, v63
	v_fma_f32 v24, v56, v44, v60
	v_fma_f32 v25, v57, v45, v61
	v_fmac_f32_dpp v38, v42, v54 row_shr:1 row_mask:0xf bank_mask:0xf
	v_fmac_f32_dpp v39, v43, v55 row_shr:1 row_mask:0xf bank_mask:0xf
	v_fmac_f32_dpp v24, v44, v52 row_shr:1 row_mask:0xf bank_mask:0xf
	v_fmac_f32_dpp v25, v45, v53 row_shr:1 row_mask:0xf bank_mask:0xf
	v_fmac_f32_dpp v38, v46, v54 row_shl:15 row_mask:0xf bank_mask:0xf
	v_fmac_f32_dpp v39, v47, v55 row_shl:15 row_mask:0xf bank_mask:0xf
	v_fmac_f32_dpp v24, v66, v52 row_shl:15 row_mask:0xf bank_mask:0xf
	v_fmac_f32_dpp v25, v67, v53 row_shl:15 row_mask:0xf bank_mask:0xf
	v_fmac_f32_dpp v38, v42, v50 row_shr:2 row_mask:0xf bank_mask:0xf
	v_fmac_f32_dpp v39, v43, v51 row_shr:2 row_mask:0xf bank_mask:0xf
	v_fmac_f32_dpp v24, v44, v48 row_shr:2 row_mask:0xf bank_mask:0xf
	v_fmac_f32_dpp v25, v45, v49 row_shr:2 row_mask:0xf bank_mask:0xf
	v_fmac_f32_dpp v38, v46, v50 row_shl:14 row_mask:0xf bank_mask:0xf
	v_fmac_f32_dpp v39, v47, v51 row_shl:14 row_mask:0xf bank_mask:0xf
	v_fmac_f32_dpp v24, v66, v48 row_shl:14 row_mask:0xf bank_mask:0xf
	v_fmac_f32_dpp v25, v67, v49 row_shl:14 row_mask:0xf bank_mask:0xf
	v_mov_b32_e32 v66, 0
	v_mov_b32_e32 v67, 0
	v_fma_f32 v26, v58, v46, v62
	v_fma_f32 v27, v59, v47, v63
	s_nop 0
	v_fmac_f32_dpp v26, v46, v54 row_shr:1 row_mask:0xf bank_mask:0xf
	v_fmac_f32_dpp v27, v47, v55 row_shr:1 row_mask:0xf bank_mask:0xf
	s_nop 0
	v_fmac_f32_dpp v26, v68, v54 row_shl:15 row_mask:0xf bank_mask:0xf
	v_fmac_f32_dpp v27, v69, v55 row_shl:15 row_mask:0xf bank_mask:0xf
	s_nop 0
	v_fmac_f32_dpp v26, v46, v50 row_shr:2 row_mask:0xf bank_mask:0xf
	v_fmac_f32_dpp v27, v47, v51 row_shr:2 row_mask:0xf bank_mask:0xf
	s_nop 0
	v_fmac_f32_dpp v26, v68, v50 row_shl:14 row_mask:0xf bank_mask:0xf
	v_fmac_f32_dpp v27, v69, v51 row_shl:14 row_mask:0xf bank_mask:0xf
	s_cbranch_vccnz .LBB0_520
	ds_read_b128 v[64:67], v201 offset:4096
; __device__ __forceinline__ float conv1(float cur, float prv, float w0, float w1, float w2, float b) {
;     float r, t1, t2;
;     asm volatile(
;         "s_nop 1\n\t"
;         "v_mov_b32_dpp %1, %4 row_ror:1 row_mask:0xf bank_mask:0xf\n\t"
;         "v_mov_b32_dpp %2, %4 row_ror:2 row_mask:0xf bank_mask:0xf\n\t"
;         "v_fma_f32 %0, %7, %3, %8\n\t"
;         "v_mov_b32_dpp %1, %3 row_shr:1 row_mask:0xf bank_mask:0xf\n\t"
;         "v_mov_b32_dpp %2, %3 row_shr:2 row_mask:0xf bank_mask:0xf\n\t"
;         "v_fmac_f32 %0, %6, %1\n\t"
;         "v_fmac_f32 %0, %5, %2\n\t"
;         : "=&v"(r), "=&v"(t1), "=&v"(t2) : "v"(cur), "v"(prv), "v"(w0), "v"(w1), "v"(w2), "v"(b));
;     return r;
; }
;     __device__ __forceinline__ void operator()(f32x4 (&acc)[2][2][4][2], const Unit& u, int wr, int wc, int fr, int fq, LAS unsigned char* xl) const {
;     ...
;         if (wr == 0 && fr < 2) {
; #pragma unroll
;             for (int s = 0; s < NS; ++s)
; #pragma unroll
;                 for (int n = 0; n < 2; ++n) *(f32x4*)(PART + (size_t)(u.pm * 2 + fr) * C + (s ? voff : 0) + ch0 + 4 * n) = acc[0][s][0][n];
.LBB0_520:
	v_pk_mul_f32 v[20:21], v[20:21], v[8:9]
	v_pk_mul_f32 v[18:19], v[18:19], v[6:7]
	v_pk_mul_f32 v[8:9], v[14:15], v[2:3]
	v_pk_mul_f32 v[6:7], v[12:13], v[0:1]
	v_pk_mul_f32 v[22:23], v[22:23], v[10:11]
	v_fma_f32 v0, v56, v128, v60
	v_fma_f32 v1, v57, v129, v61
	v_fma_f32 v2, v58, v130, v62
	v_fma_f32 v3, v59, v131, v63
	v_fmac_f32_dpp v0, v128, v52 row_shr:1 row_mask:0xf bank_mask:0xf
	v_fmac_f32_dpp v1, v129, v53 row_shr:1 row_mask:0xf bank_mask:0xf
	v_fmac_f32_dpp v2, v130, v54 row_shr:1 row_mask:0xf bank_mask:0xf
	v_fmac_f32_dpp v3, v131, v55 row_shr:1 row_mask:0xf bank_mask:0xf
	v_fmac_f32_dpp v0, v6, v52 row_shl:15 row_mask:0xf bank_mask:0xf
	v_fmac_f32_dpp v1, v7, v53 row_shl:15 row_mask:0xf bank_mask:0xf
	v_fmac_f32_dpp v2, v8, v54 row_shl:15 row_mask:0xf bank_mask:0xf
	v_fmac_f32_dpp v3, v9, v55 row_shl:15 row_mask:0xf bank_mask:0xf
	v_fmac_f32_dpp v0, v128, v48 row_shr:2 row_mask:0xf bank_mask:0xf
	v_fmac_f32_dpp v1, v129, v49 row_shr:2 row_mask:0xf bank_mask:0xf
	v_fmac_f32_dpp v2, v130, v50 row_shr:2 row_mask:0xf bank_mask:0xf
	v_fmac_f32_dpp v3, v131, v51 row_shr:2 row_mask:0xf bank_mask:0xf
	v_fmac_f32_dpp v0, v6, v48 row_shl:14 row_mask:0xf bank_mask:0xf
	v_fmac_f32_dpp v1, v7, v49 row_shl:14 row_mask:0xf bank_mask:0xf
	v_fmac_f32_dpp v2, v8, v50 row_shl:14 row_mask:0xf bank_mask:0xf
	v_fmac_f32_dpp v3, v9, v51 row_shl:14 row_mask:0xf bank_mask:0xf
	v_pk_mul_f32 v[10:11], v[16:17], v[4:5]
	s_nop 0
	v_fma_f32 v4, v56, v6, v60
	v_fma_f32 v5, v57, v7, v61
	s_nop 0
	v_fmac_f32_dpp v4, v6, v52 row_shr:1 row_mask:0xf bank_mask:0xf
	v_fmac_f32_dpp v5, v7, v53 row_shr:1 row_mask:0xf bank_mask:0xf
	s_nop 0
	v_fmac_f32_dpp v4, v10, v52 row_shl:15 row_mask:0xf bank_mask:0xf
	v_fmac_f32_dpp v5, v11, v53 row_shl:15 row_mask:0xf bank_mask:0xf
	s_nop 0
	v_fmac_f32_dpp v4, v6, v48 row_shr:2 row_mask:0xf bank_mask:0xf
	v_fmac_f32_dpp v5, v7, v49 row_shr:2 row_mask:0xf bank_mask:0xf
	s_nop 0
	v_fmac_f32_dpp v4, v10, v48 row_shl:14 row_mask:0xf bank_mask:0xf
	v_fmac_f32_dpp v5, v11, v49 row_shl:14 row_mask:0xf bank_mask:0xf
	s_nop 0
	v_fma_f32 v6, v58, v8, v62
	v_fma_f32 v7, v59, v9, v63
	s_nop 0
	v_fmac_f32_dpp v6, v8, v54 row_shr:1 row_mask:0xf bank_mask:0xf
	v_fmac_f32_dpp v7, v9, v55 row_shr:1 row_mask:0xf bank_mask:0xf
	s_nop 0
	v_fmac_f32_dpp v6, v18, v54 row_shl:15 row_mask:0xf bank_mask:0xf
	v_fmac_f32_dpp v7, v19, v55 row_shl:15 row_mask:0xf bank_mask:0xf
	s_nop 0
	v_fmac_f32_dpp v6, v8, v50 row_shr:2 row_mask:0xf bank_mask:0xf
	v_fmac_f32_dpp v7, v9, v51 row_shr:2 row_mask:0xf bank_mask:0xf
	s_nop 0
	v_fmac_f32_dpp v6, v18, v50 row_shl:14 row_mask:0xf bank_mask:0xf
	v_fmac_f32_dpp v7, v19, v51 row_shl:14 row_mask:0xf bank_mask:0xf
	s_nop 0
	v_fma_f32 v8, v56, v10, v60
	v_fma_f32 v9, v57, v11, v61
	s_nop 0
	v_fmac_f32_dpp v8, v10, v52 row_shr:1 row_mask:0xf bank_mask:0xf
	v_fmac_f32_dpp v9, v11, v53 row_shr:1 row_mask:0xf bank_mask:0xf
	s_nop 0
	v_fmac_f32_dpp v8, v20, v52 row_shl:15 row_mask:0xf bank_mask:0xf
	v_fmac_f32_dpp v9, v21, v53 row_shl:15 row_mask:0xf bank_mask:0xf
	s_nop 0
	v_fmac_f32_dpp v8, v10, v48 row_shr:2 row_mask:0xf bank_mask:0xf
	v_fmac_f32_dpp v9, v11, v49 row_shr:2 row_mask:0xf bank_mask:0xf
	s_nop 0
	v_fmac_f32_dpp v8, v20, v48 row_shl:14 row_mask:0xf bank_mask:0xf
	v_fmac_f32_dpp v9, v21, v49 row_shl:14 row_mask:0xf bank_mask:0xf
	s_nop 0
	v_fma_f32 v10, v58, v18, v62
	v_fma_f32 v11, v59, v19, v63
	s_nop 0
	v_fmac_f32_dpp v10, v18, v54 row_shr:1 row_mask:0xf bank_mask:0xf
	v_fmac_f32_dpp v11, v19, v55 row_shr:1 row_mask:0xf bank_mask:0xf
	s_nop 0
	v_fmac_f32_dpp v10, v22, v54 row_shl:15 row_mask:0xf bank_mask:0xf
	v_fmac_f32_dpp v11, v23, v55 row_shl:15 row_mask:0xf bank_mask:0xf
	s_nop 0
	v_fmac_f32_dpp v10, v18, v50 row_shr:2 row_mask:0xf bank_mask:0xf
	v_fmac_f32_dpp v11, v19, v51 row_shr:2 row_mask:0xf bank_mask:0xf
	s_nop 0
	v_fmac_f32_dpp v10, v22, v50 row_shl:14 row_mask:0xf bank_mask:0xf
	v_fmac_f32_dpp v11, v23, v51 row_shl:14 row_mask:0xf bank_mask:0xf
	s_waitcnt lgkmcnt(0)
	v_fma_f32 v12, v56, v20, v60
	v_fma_f32 v13, v57, v21, v61
	v_fma_f32 v14, v58, v22, v62
	v_fma_f32 v15, v59, v23, v63
	v_fmac_f32_dpp v12, v20, v52 row_shr:1 row_mask:0xf bank_mask:0xf
	v_fmac_f32_dpp v13, v21, v53 row_shr:1 row_mask:0xf bank_mask:0xf
	v_fmac_f32_dpp v14, v22, v54 row_shr:1 row_mask:0xf bank_mask:0xf
	v_fmac_f32_dpp v15, v23, v55 row_shr:1 row_mask:0xf bank_mask:0xf
	v_fmac_f32_dpp v12, v64, v52 row_shl:15 row_mask:0xf bank_mask:0xf
	v_fmac_f32_dpp v13, v65, v53 row_shl:15 row_mask:0xf bank_mask:0xf
	v_fmac_f32_dpp v14, v66, v54 row_shl:15 row_mask:0xf bank_mask:0xf
	v_fmac_f32_dpp v15, v67, v55 row_shl:15 row_mask:0xf bank_mask:0xf
	v_fmac_f32_dpp v12, v20, v48 row_shr:2 row_mask:0xf bank_mask:0xf
	v_fmac_f32_dpp v13, v21, v49 row_shr:2 row_mask:0xf bank_mask:0xf
	v_fmac_f32_dpp v14, v22, v50 row_shr:2 row_mask:0xf bank_mask:0xf
	v_fmac_f32_dpp v15, v23, v51 row_shr:2 row_mask:0xf bank_mask:0xf
	v_fmac_f32_dpp v12, v64, v48 row_shl:14 row_mask:0xf bank_mask:0xf
	v_fmac_f32_dpp v13, v65, v49 row_shl:14 row_mask:0xf bank_mask:0xf
	v_fmac_f32_dpp v14, v66, v50 row_shl:14 row_mask:0xf bank_mask:0xf
	v_fmac_f32_dpp v15, v67, v51 row_shl:14 row_mask:0xf bank_mask:0xf
	s_and_saveexec_b64 s[8:9], s[66:67]
	s_cbranch_execz .LBB0_498
	v_lshl_or_b32 v16, s50, 1, v169
	v_ashrrev_i32_e32 v17, 31, v16
	v_lshlrev_b64 v[16:17], 13, v[16:17]
	v_lshl_add_u64 v[16:17], s[54:55], 0, v[16:17]
	v_lshl_add_u64 v[16:17], v[166:167], 2, v[16:17]
	global_store_dwordx4 v[16:17], v[72:75], off
	global_store_dwordx4 v[16:17], v[24:27], off offset:16
	s_branch .LBB0_498

; #define LAS __attribute__((address_space(3)))
; __device__ __forceinline__ float conv1(float cur, float prv, float w0, float w1, float w2, float b) {
;     float r, t1, t2;
;     asm volatile(
;         "s_nop 1\n\t"
;         "v_mov_b32_dpp %1, %4 row_ror:1 row_mask:0xf bank_mask:0xf\n\t"
;         "v_mov_b32_dpp %2, %4 row_ror:2 row_mask:0xf bank_mask:0xf\n\t"
;         "v_fma_f32 %0, %7, %3, %8\n\t"
;         "v_mov_b32_dpp %1, %3 row_shr:1 row_mask:0xf bank_mask:0xf\n\t"
;         "v_mov_b32_dpp %2, %3 row_shr:2 row_mask:0xf bank_mask:0xf\n\t"
;         "v_fmac_f32 %0, %6, %1\n\t"
;         "v_fmac_f32 %0, %5, %2\n\t"
;         : "=&v"(r), "=&v"(t1), "=&v"(t2) : "v"(cur), "v"(prv), "v"(w0), "v"(w1), "v"(w2), "v"(b));
;     return r;
; }
;     __device__ __forceinline__ void operator()(f32x4 (&acc)[2][2][4][2], const Unit& u, int wr, int wc, int fr, int fq, LAS unsigned char* xl) const {
;     ...
;             for (int n = 0; n < 2; ++n) {
;                 const int lc = s * 128 + chl + 4 * n;
;                 const f32x4 w0 = *(const LAS f32x4*)(wt + lc), w1 = *(const LAS f32x4*)(wt + 256 + lc), w2 = *(const LAS f32x4*)(wt + 512 + lc), bb = *(const LAS f32x4*)(wt + 768 + lc);
; #pragma unroll
;                 for (int ai = 0; ai < 2; ++ai) {
;                     const int blk = ai * 2 + wr;
;                     f32x4 pg = (f32x4){0.f, 0.f, 0.f, 0.f};
;                     if (blk > 0) pg = *(const LAS f32x4*)(bnd + (((blk - 1) * 2 + (fr & 1)) * 256 + lc));
; #pragma unroll
;                     for (int m = 3; m >= 0; --m) acc[ai][s][m][n] = conv3(acc[ai][s][m][n], m == 0 ? pg : acc[ai][s][m - 1][n], w0, w1, w2, bb);
.LBB0_746:
	s_waitcnt lgkmcnt(0)
	v_fma_f32 v204, v136, v124, v140
	v_fma_f32 v202, v137, v125, v141
	v_fma_f32 v201, v138, v126, v142
	v_fma_f32 v200, v139, v127, v143
	v_fmac_f32_dpp v204, v124, v132 row_shr:1 row_mask:0xf bank_mask:0xf
	v_fmac_f32_dpp v202, v125, v133 row_shr:1 row_mask:0xf bank_mask:0xf
	v_fmac_f32_dpp v201, v126, v134 row_shr:1 row_mask:0xf bank_mask:0xf
	v_fmac_f32_dpp v200, v127, v135 row_shr:1 row_mask:0xf bank_mask:0xf
	v_fmac_f32_dpp v204, v120, v132 row_shl:15 row_mask:0xf bank_mask:0xf
	v_fmac_f32_dpp v202, v121, v133 row_shl:15 row_mask:0xf bank_mask:0xf
	v_fmac_f32_dpp v201, v122, v134 row_shl:15 row_mask:0xf bank_mask:0xf
	v_fmac_f32_dpp v200, v123, v135 row_shl:15 row_mask:0xf bank_mask:0xf
	v_fmac_f32_dpp v204, v124, v128 row_shr:2 row_mask:0xf bank_mask:0xf
	v_fmac_f32_dpp v202, v125, v129 row_shr:2 row_mask:0xf bank_mask:0xf
	v_fmac_f32_dpp v201, v126, v130 row_shr:2 row_mask:0xf bank_mask:0xf
	v_fmac_f32_dpp v200, v127, v131 row_shr:2 row_mask:0xf bank_mask:0xf
	v_fmac_f32_dpp v204, v120, v128 row_shl:14 row_mask:0xf bank_mask:0xf
	v_fmac_f32_dpp v202, v121, v129 row_shl:14 row_mask:0xf bank_mask:0xf
	v_fmac_f32_dpp v201, v122, v130 row_shl:14 row_mask:0xf bank_mask:0xf
	v_fmac_f32_dpp v200, v123, v131 row_shl:14 row_mask:0xf bank_mask:0xf
	s_andn2_b64 vcc, exec, s[64:65]
	v_mov_b32_e32 v145, 0
	s_nop 0
	v_fma_f32 v208, v136, v120, v140
	v_fma_f32 v207, v137, v121, v141
	v_fma_f32 v206, v138, v122, v142
	v_fma_f32 v205, v139, v123, v143
	v_fmac_f32_dpp v208, v120, v132 row_shr:1 row_mask:0xf bank_mask:0xf
	v_fmac_f32_dpp v207, v121, v133 row_shr:1 row_mask:0xf bank_mask:0xf
	v_fmac_f32_dpp v206, v122, v134 row_shr:1 row_mask:0xf bank_mask:0xf
	v_fmac_f32_dpp v205, v123, v135 row_shr:1 row_mask:0xf bank_mask:0xf
	v_fmac_f32_dpp v208, v88, v132 row_shl:15 row_mask:0xf bank_mask:0xf
	v_fmac_f32_dpp v207, v89, v133 row_shl:15 row_mask:0xf bank_mask:0xf
	v_fmac_f32_dpp v206, v90, v134 row_shl:15 row_mask:0xf bank_mask:0xf
	v_fmac_f32_dpp v205, v91, v135 row_shl:15 row_mask:0xf bank_mask:0xf
	v_fmac_f32_dpp v208, v120, v128 row_shr:2 row_mask:0xf bank_mask:0xf
	v_fmac_f32_dpp v207, v121, v129 row_shr:2 row_mask:0xf bank_mask:0xf
	v_fmac_f32_dpp v206, v122, v130 row_shr:2 row_mask:0xf bank_mask:0xf
	v_fmac_f32_dpp v205, v123, v131 row_shr:2 row_mask:0xf bank_mask:0xf
	v_fmac_f32_dpp v208, v88, v128 row_shl:14 row_mask:0xf bank_mask:0xf
	v_fmac_f32_dpp v207, v89, v129 row_shl:14 row_mask:0xf bank_mask:0xf
	v_fmac_f32_dpp v206, v90, v130 row_shl:14 row_mask:0xf bank_mask:0xf
	v_fmac_f32_dpp v205, v91, v131 row_shl:14 row_mask:0xf bank_mask:0xf
	s_nop 0
	v_fma_f32 v212, v136, v88, v140
	v_fma_f32 v211, v137, v89, v141
	v_fma_f32 v210, v138, v90, v142
	v_fma_f32 v209, v139, v91, v143
	v_fmac_f32_dpp v212, v88, v132 row_shr:1 row_mask:0xf bank_mask:0xf
	v_fmac_f32_dpp v211, v89, v133 row_shr:1 row_mask:0xf bank_mask:0xf
	v_fmac_f32_dpp v210, v90, v134 row_shr:1 row_mask:0xf bank_mask:0xf
	v_fmac_f32_dpp v209, v91, v135 row_shr:1 row_mask:0xf bank_mask:0xf
	v_fmac_f32_dpp v212, v116, v132 row_shl:15 row_mask:0xf bank_mask:0xf
	v_fmac_f32_dpp v211, v117, v133 row_shl:15 row_mask:0xf bank_mask:0xf
	v_fmac_f32_dpp v210, v118, v134 row_shl:15 row_mask:0xf bank_mask:0xf
	v_fmac_f32_dpp v209, v119, v135 row_shl:15 row_mask:0xf bank_mask:0xf
	v_fmac_f32_dpp v212, v88, v128 row_shr:2 row_mask:0xf bank_mask:0xf
	v_fmac_f32_dpp v211, v89, v129 row_shr:2 row_mask:0xf bank_mask:0xf
	v_fmac_f32_dpp v210, v90, v130 row_shr:2 row_mask:0xf bank_mask:0xf
	v_fmac_f32_dpp v209, v91, v131 row_shr:2 row_mask:0xf bank_mask:0xf
	v_fmac_f32_dpp v212, v116, v128 row_shl:14 row_mask:0xf bank_mask:0xf
	v_fmac_f32_dpp v211, v117, v129 row_shl:14 row_mask:0xf bank_mask:0xf
	v_fmac_f32_dpp v210, v118, v130 row_shl:14 row_mask:0xf bank_mask:0xf
	v_fmac_f32_dpp v209, v119, v131 row_shl:14 row_mask:0xf bank_mask:0xf
	s_nop 0
	v_fma_f32 v88, v136, v116, v140
	v_fma_f32 v89, v137, v117, v141
	v_fma_f32 v90, v138, v118, v142
	v_fma_f32 v91, v139, v119, v143
	v_fmac_f32_dpp v88, v116, v132 row_shr:1 row_mask:0xf bank_mask:0xf
	v_fmac_f32_dpp v89, v117, v133 row_shr:1 row_mask:0xf bank_mask:0xf
	v_fmac_f32_dpp v90, v118, v134 row_shr:1 row_mask:0xf bank_mask:0xf
	v_fmac_f32_dpp v91, v119, v135 row_shr:1 row_mask:0xf bank_mask:0xf
	v_fmac_f32_dpp v88, v146, v132 row_shl:15 row_mask:0xf bank_mask:0xf
	v_fmac_f32_dpp v89, v147, v133 row_shl:15 row_mask:0xf bank_mask:0xf
	v_fmac_f32_dpp v90, v148, v134 row_shl:15 row_mask:0xf bank_mask:0xf
	v_fmac_f32_dpp v91, v149, v135 row_shl:15 row_mask:0xf bank_mask:0xf
	v_fmac_f32_dpp v88, v116, v128 row_shr:2 row_mask:0xf bank_mask:0xf
	v_fmac_f32_dpp v89, v117, v129 row_shr:2 row_mask:0xf bank_mask:0xf
	v_fmac_f32_dpp v90, v118, v130 row_shr:2 row_mask:0xf bank_mask:0xf
	v_fmac_f32_dpp v91, v119, v131 row_shr:2 row_mask:0xf bank_mask:0xf
	v_fmac_f32_dpp v88, v146, v128 row_shl:14 row_mask:0xf bank_mask:0xf
	v_fmac_f32_dpp v89, v147, v129 row_shl:14 row_mask:0xf bank_mask:0xf
	v_fmac_f32_dpp v90, v148, v130 row_shl:14 row_mask:0xf bank_mask:0xf
	v_fmac_f32_dpp v91, v149, v131 row_shl:14 row_mask:0xf bank_mask:0xf
	v_mov_b32_e32 v146, 0
	v_mov_b32_e32 v147, 0
	s_nop 0
	v_cndmask_b32_e64 v116, 0, 1, s[64:65]
	v_cmp_ne_u32_e64 s[8:9], 1, v116
	s_cbranch_vccnz .LBB0_748
	ds_read_b128 v[144:147], v183 offset:4096
; #define LAS __attribute__((address_space(3)))
; __device__ __forceinline__ float conv1(float cur, float prv, float w0, float w1, float w2, float b) {
;     float r, t1, t2;
;     asm volatile(
;         "s_nop 1\n\t"
;         "v_mov_b32_dpp %1, %4 row_ror:1 row_mask:0xf bank_mask:0xf\n\t"
;         "v_mov_b32_dpp %2, %4 row_ror:2 row_mask:0xf bank_mask:0xf\n\t"
;         "v_fma_f32 %0, %7, %3, %8\n\t"
;         "v_mov_b32_dpp %1, %3 row_shr:1 row_mask:0xf bank_mask:0xf\n\t"
;         "v_mov_b32_dpp %2, %3 row_shr:2 row_mask:0xf bank_mask:0xf\n\t"
;         "v_fmac_f32 %0, %6, %1\n\t"
;         "v_fmac_f32 %0, %5, %2\n\t"
;         : "=&v"(r), "=&v"(t1), "=&v"(t2) : "v"(cur), "v"(prv), "v"(w0), "v"(w1), "v"(w2), "v"(b));
;     return r;
; }
;     __device__ __forceinline__ void operator()(f32x4 (&acc)[2][2][4][2], const Unit& u, int wr, int wc, int fr, int fq, LAS unsigned char* xl) const {
;     ...
;             for (int n = 0; n < 2; ++n) {
;                 const int lc = s * 128 + chl + 4 * n;
;                 const f32x4 w0 = *(const LAS f32x4*)(wt + lc), w1 = *(const LAS f32x4*)(wt + 256 + lc), w2 = *(const LAS f32x4*)(wt + 512 + lc), bb = *(const LAS f32x4*)(wt + 768 + lc);
; #pragma unroll
;                 for (int ai = 0; ai < 2; ++ai) {
;                     const int blk = ai * 2 + wr;
;                     f32x4 pg = (f32x4){0.f, 0.f, 0.f, 0.f};
;                     if (blk > 0) pg = *(const LAS f32x4*)(bnd + (((blk - 1) * 2 + (fr & 1)) * 256 + lc));
; #pragma unroll
;                     for (int m = 3; m >= 0; --m) acc[ai][s][m][n] = conv3(acc[ai][s][m][n], m == 0 ? pg : acc[ai][s][m - 1][n], w0, w1, w2, bb);
.LBB0_748:
	v_fma_f32 v125, v136, v112, v140
	v_fma_f32 v124, v137, v113, v141
	v_fma_f32 v123, v138, v114, v142
	v_fma_f32 v122, v139, v115, v143
	v_fmac_f32_dpp v125, v112, v132 row_shr:1 row_mask:0xf bank_mask:0xf
	v_fmac_f32_dpp v124, v113, v133 row_shr:1 row_mask:0xf bank_mask:0xf
	v_fmac_f32_dpp v123, v114, v134 row_shr:1 row_mask:0xf bank_mask:0xf
	v_fmac_f32_dpp v122, v115, v135 row_shr:1 row_mask:0xf bank_mask:0xf
	v_fmac_f32_dpp v125, v108, v132 row_shl:15 row_mask:0xf bank_mask:0xf
	v_fmac_f32_dpp v124, v109, v133 row_shl:15 row_mask:0xf bank_mask:0xf
	v_fmac_f32_dpp v123, v110, v134 row_shl:15 row_mask:0xf bank_mask:0xf
	v_fmac_f32_dpp v122, v111, v135 row_shl:15 row_mask:0xf bank_mask:0xf
	v_fmac_f32_dpp v125, v112, v128 row_shr:2 row_mask:0xf bank_mask:0xf
	v_fmac_f32_dpp v124, v113, v129 row_shr:2 row_mask:0xf bank_mask:0xf
	v_fmac_f32_dpp v123, v114, v130 row_shr:2 row_mask:0xf bank_mask:0xf
	v_fmac_f32_dpp v122, v115, v131 row_shr:2 row_mask:0xf bank_mask:0xf
	v_fmac_f32_dpp v125, v108, v128 row_shl:14 row_mask:0xf bank_mask:0xf
	v_fmac_f32_dpp v124, v109, v129 row_shl:14 row_mask:0xf bank_mask:0xf
	v_fmac_f32_dpp v123, v110, v130 row_shl:14 row_mask:0xf bank_mask:0xf
	v_fmac_f32_dpp v122, v111, v131 row_shl:14 row_mask:0xf bank_mask:0xf
	s_nop 0
	v_fma_f32 v149, v136, v108, v140
	v_fma_f32 v148, v137, v109, v141
	v_fma_f32 v127, v138, v110, v142
	v_fma_f32 v126, v139, v111, v143
	v_fmac_f32_dpp v149, v108, v132 row_shr:1 row_mask:0xf bank_mask:0xf
	v_fmac_f32_dpp v148, v109, v133 row_shr:1 row_mask:0xf bank_mask:0xf
	v_fmac_f32_dpp v127, v110, v134 row_shr:1 row_mask:0xf bank_mask:0xf
	v_fmac_f32_dpp v126, v111, v135 row_shr:1 row_mask:0xf bank_mask:0xf
	v_fmac_f32_dpp v149, v104, v132 row_shl:15 row_mask:0xf bank_mask:0xf
	v_fmac_f32_dpp v148, v105, v133 row_shl:15 row_mask:0xf bank_mask:0xf
	v_fmac_f32_dpp v127, v106, v134 row_shl:15 row_mask:0xf bank_mask:0xf
	v_fmac_f32_dpp v126, v107, v135 row_shl:15 row_mask:0xf bank_mask:0xf
	v_fmac_f32_dpp v149, v108, v128 row_shr:2 row_mask:0xf bank_mask:0xf
	v_fmac_f32_dpp v148, v109, v129 row_shr:2 row_mask:0xf bank_mask:0xf
	v_fmac_f32_dpp v127, v110, v130 row_shr:2 row_mask:0xf bank_mask:0xf
	v_fmac_f32_dpp v126, v111, v131 row_shr:2 row_mask:0xf bank_mask:0xf
	v_fmac_f32_dpp v149, v104, v128 row_shl:14 row_mask:0xf bank_mask:0xf
	v_fmac_f32_dpp v148, v105, v129 row_shl:14 row_mask:0xf bank_mask:0xf
	v_fmac_f32_dpp v127, v106, v130 row_shl:14 row_mask:0xf bank_mask:0xf
	v_fmac_f32_dpp v126, v107, v131 row_shl:14 row_mask:0xf bank_mask:0xf
	s_nop 0
	v_fma_f32 v187, v136, v104, v140
	v_fma_f32 v186, v137, v105, v141
	v_fma_f32 v185, v138, v106, v142
	v_fma_f32 v184, v139, v107, v143
	v_fmac_f32_dpp v187, v104, v132 row_shr:1 row_mask:0xf bank_mask:0xf
	v_fmac_f32_dpp v186, v105, v133 row_shr:1 row_mask:0xf bank_mask:0xf
	v_fmac_f32_dpp v185, v106, v134 row_shr:1 row_mask:0xf bank_mask:0xf
	v_fmac_f32_dpp v184, v107, v135 row_shr:1 row_mask:0xf bank_mask:0xf
	v_fmac_f32_dpp v187, v100, v132 row_shl:15 row_mask:0xf bank_mask:0xf
	v_fmac_f32_dpp v186, v101, v133 row_shl:15 row_mask:0xf bank_mask:0xf
	v_fmac_f32_dpp v185, v102, v134 row_shl:15 row_mask:0xf bank_mask:0xf
	v_fmac_f32_dpp v184, v103, v135 row_shl:15 row_mask:0xf bank_mask:0xf
	v_fmac_f32_dpp v187, v104, v128 row_shr:2 row_mask:0xf bank_mask:0xf
	v_fmac_f32_dpp v186, v105, v129 row_shr:2 row_mask:0xf bank_mask:0xf
	v_fmac_f32_dpp v185, v106, v130 row_shr:2 row_mask:0xf bank_mask:0xf
	v_fmac_f32_dpp v184, v107, v131 row_shr:2 row_mask:0xf bank_mask:0xf
	v_fmac_f32_dpp v187, v100, v128 row_shl:14 row_mask:0xf bank_mask:0xf
	v_fmac_f32_dpp v186, v101, v129 row_shl:14 row_mask:0xf bank_mask:0xf
	v_fmac_f32_dpp v185, v102, v130 row_shl:14 row_mask:0xf bank_mask:0xf
	v_fmac_f32_dpp v184, v103, v131 row_shl:14 row_mask:0xf bank_mask:0xf
	s_waitcnt lgkmcnt(0)
	s_nop 0
	v_fma_f32 v203, v136, v100, v140
	s_nop 1
	v_fmac_f32_dpp v203, v100, v132 row_shr:1 row_mask:0xf bank_mask:0xf
	s_nop 1
	v_fmac_f32_dpp v203, v144, v132 row_shl:15 row_mask:0xf bank_mask:0xf
	s_nop 1
	v_fmac_f32_dpp v203, v100, v128 row_shr:2 row_mask:0xf bank_mask:0xf
	s_nop 1
	v_fmac_f32_dpp v203, v144, v128 row_shl:14 row_mask:0xf bank_mask:0xf
	s_nop 0
	s_nop 0
	v_fma_f32 v136, v137, v101, v141
	s_nop 1
	v_fmac_f32_dpp v136, v101, v133 row_shr:1 row_mask:0xf bank_mask:0xf
	s_nop 1
	v_fmac_f32_dpp v136, v145, v133 row_shl:15 row_mask:0xf bank_mask:0xf
	s_nop 1
	v_fmac_f32_dpp v136, v101, v129 row_shr:2 row_mask:0xf bank_mask:0xf
	s_nop 1
	v_fmac_f32_dpp v136, v145, v129 row_shl:14 row_mask:0xf bank_mask:0xf
	s_nop 0
	v_fma_f32 v133, v138, v102, v142
	v_fma_f32 v132, v139, v103, v143
	s_nop 0
	v_fmac_f32_dpp v133, v102, v134 row_shr:1 row_mask:0xf bank_mask:0xf
	v_fmac_f32_dpp v132, v103, v135 row_shr:1 row_mask:0xf bank_mask:0xf
	s_nop 0
	v_fmac_f32_dpp v133, v146, v134 row_shl:15 row_mask:0xf bank_mask:0xf
	v_fmac_f32_dpp v132, v147, v135 row_shl:15 row_mask:0xf bank_mask:0xf
	s_nop 0
	v_fmac_f32_dpp v133, v102, v130 row_shr:2 row_mask:0xf bank_mask:0xf
	v_fmac_f32_dpp v132, v103, v131 row_shr:2 row_mask:0xf bank_mask:0xf
	s_nop 0
	v_fmac_f32_dpp v133, v146, v130 row_shl:14 row_mask:0xf bank_mask:0xf
	v_fmac_f32_dpp v132, v147, v131 row_shl:14 row_mask:0xf bank_mask:0xf
	ds_read_b128 v[100:103], v161
	ds_read_b128 v[104:107], v162
	ds_read_b128 v[108:111], v163
	ds_read_b128 v[112:115], v164
	v_cndmask_b32_e64 v117, 0, 1, s[60:61]
	v_mov_b32_e32 v116, 0
	v_cmp_ne_u32_e64 s[10:11], 1, v117
	s_andn2_b64 vcc, exec, s[60:61]
	v_mov_b32_e32 v118, 0
	v_mov_b32_e32 v119, 0
	v_mov_b32_e32 v120, 0
	v_mov_b32_e32 v121, 0
	s_cbranch_vccnz .LBB0_750
	ds_read_b128 v[118:121], v165
; #define LAS __attribute__((address_space(3)))
; __device__ __forceinline__ float conv1(float cur, float prv, float w0, float w1, float w2, float b) {
;     float r, t1, t2;
;     asm volatile(
;         "s_nop 1\n\t"
;         "v_mov_b32_dpp %1, %4 row_ror:1 row_mask:0xf bank_mask:0xf\n\t"
;         "v_mov_b32_dpp %2, %4 row_ror:2 row_mask:0xf bank_mask:0xf\n\t"
;         "v_fma_f32 %0, %7, %3, %8\n\t"
;         "v_mov_b32_dpp %1, %3 row_shr:1 row_mask:0xf bank_mask:0xf\n\t"
;         "v_mov_b32_dpp %2, %3 row_shr:2 row_mask:0xf bank_mask:0xf\n\t"
;         "v_fmac_f32 %0, %6, %1\n\t"
;         "v_fmac_f32 %0, %5, %2\n\t"
;         : "=&v"(r), "=&v"(t1), "=&v"(t2) : "v"(cur), "v"(prv), "v"(w0), "v"(w1), "v"(w2), "v"(b));
;     return r;
; }
;     __device__ __forceinline__ void operator()(f32x4 (&acc)[2][2][4][2], const Unit& u, int wr, int wc, int fr, int fq, LAS unsigned char* xl) const {
;     ...
;             for (int n = 0; n < 2; ++n) {
;                 const int lc = s * 128 + chl + 4 * n;
;                 const f32x4 w0 = *(const LAS f32x4*)(wt + lc), w1 = *(const LAS f32x4*)(wt + 256 + lc), w2 = *(const LAS f32x4*)(wt + 512 + lc), bb = *(const LAS f32x4*)(wt + 768 + lc);
; #pragma unroll
;                 for (int ai = 0; ai < 2; ++ai) {
;                     const int blk = ai * 2 + wr;
;                     f32x4 pg = (f32x4){0.f, 0.f, 0.f, 0.f};
;                     if (blk > 0) pg = *(const LAS f32x4*)(bnd + (((blk - 1) * 2 + (fr & 1)) * 256 + lc));
; #pragma unroll
;                     for (int m = 3; m >= 0; --m) acc[ai][s][m][n] = conv3(acc[ai][s][m][n], m == 0 ? pg : acc[ai][s][m - 1][n], w0, w1, w2, bb);
.LBB0_750:
	s_waitcnt lgkmcnt(0)
	v_fma_f32 v141, v108, v96, v112
	v_fma_f32 v139, v109, v97, v113
	v_fma_f32 v138, v110, v98, v114
	v_fma_f32 v137, v111, v99, v115
	v_fmac_f32_dpp v141, v96, v104 row_shr:1 row_mask:0xf bank_mask:0xf
	v_fmac_f32_dpp v139, v97, v105 row_shr:1 row_mask:0xf bank_mask:0xf
	v_fmac_f32_dpp v138, v98, v106 row_shr:1 row_mask:0xf bank_mask:0xf
	v_fmac_f32_dpp v137, v99, v107 row_shr:1 row_mask:0xf bank_mask:0xf
	v_fmac_f32_dpp v141, v92, v104 row_shl:15 row_mask:0xf bank_mask:0xf
	v_fmac_f32_dpp v139, v93, v105 row_shl:15 row_mask:0xf bank_mask:0xf
	v_fmac_f32_dpp v138, v94, v106 row_shl:15 row_mask:0xf bank_mask:0xf
	v_fmac_f32_dpp v137, v95, v107 row_shl:15 row_mask:0xf bank_mask:0xf
	v_fmac_f32_dpp v141, v96, v100 row_shr:2 row_mask:0xf bank_mask:0xf
	v_fmac_f32_dpp v139, v97, v101 row_shr:2 row_mask:0xf bank_mask:0xf
	v_fmac_f32_dpp v138, v98, v102 row_shr:2 row_mask:0xf bank_mask:0xf
	v_fmac_f32_dpp v137, v99, v103 row_shr:2 row_mask:0xf bank_mask:0xf
	v_fmac_f32_dpp v141, v92, v100 row_shl:14 row_mask:0xf bank_mask:0xf
	v_fmac_f32_dpp v139, v93, v101 row_shl:14 row_mask:0xf bank_mask:0xf
	v_fmac_f32_dpp v138, v94, v102 row_shl:14 row_mask:0xf bank_mask:0xf
	v_fmac_f32_dpp v137, v95, v103 row_shl:14 row_mask:0xf bank_mask:0xf
	s_and_b64 vcc, exec, s[8:9]
	v_mov_b32_e32 v117, 0
	s_nop 0
	v_fma_f32 v145, v108, v92, v112
	v_fma_f32 v144, v109, v93, v113
	v_fma_f32 v143, v110, v94, v114
	v_fma_f32 v142, v111, v95, v115
	v_fmac_f32_dpp v145, v92, v104 row_shr:1 row_mask:0xf bank_mask:0xf
	v_fmac_f32_dpp v144, v93, v105 row_shr:1 row_mask:0xf bank_mask:0xf
	v_fmac_f32_dpp v143, v94, v106 row_shr:1 row_mask:0xf bank_mask:0xf
	v_fmac_f32_dpp v142, v95, v107 row_shr:1 row_mask:0xf bank_mask:0xf
	v_fmac_f32_dpp v145, v84, v104 row_shl:15 row_mask:0xf bank_mask:0xf
	v_fmac_f32_dpp v144, v85, v105 row_shl:15 row_mask:0xf bank_mask:0xf
	v_fmac_f32_dpp v143, v86, v106 row_shl:15 row_mask:0xf bank_mask:0xf
	v_fmac_f32_dpp v142, v87, v107 row_shl:15 row_mask:0xf bank_mask:0xf
	v_fmac_f32_dpp v145, v92, v100 row_shr:2 row_mask:0xf bank_mask:0xf
	v_fmac_f32_dpp v144, v93, v101 row_shr:2 row_mask:0xf bank_mask:0xf
	v_fmac_f32_dpp v143, v94, v102 row_shr:2 row_mask:0xf bank_mask:0xf
	v_fmac_f32_dpp v142, v95, v103 row_shr:2 row_mask:0xf bank_mask:0xf
	v_fmac_f32_dpp v145, v84, v100 row_shl:14 row_mask:0xf bank_mask:0xf
	v_fmac_f32_dpp v144, v85, v101 row_shl:14 row_mask:0xf bank_mask:0xf
	v_fmac_f32_dpp v143, v86, v102 row_shl:14 row_mask:0xf bank_mask:0xf
	v_fmac_f32_dpp v142, v87, v103 row_shl:14 row_mask:0xf bank_mask:0xf
	s_nop 0
	v_fma_f32 v214, v108, v84, v112
	v_fma_f32 v213, v109, v85, v113
	v_fma_f32 v147, v110, v86, v114
	v_fma_f32 v146, v111, v87, v115
	v_fmac_f32_dpp v214, v84, v104 row_shr:1 row_mask:0xf bank_mask:0xf
	v_fmac_f32_dpp v213, v85, v105 row_shr:1 row_mask:0xf bank_mask:0xf
	v_fmac_f32_dpp v147, v86, v106 row_shr:1 row_mask:0xf bank_mask:0xf
	v_fmac_f32_dpp v146, v87, v107 row_shr:1 row_mask:0xf bank_mask:0xf
	v_fmac_f32_dpp v214, v80, v104 row_shl:15 row_mask:0xf bank_mask:0xf
	v_fmac_f32_dpp v213, v81, v105 row_shl:15 row_mask:0xf bank_mask:0xf
	v_fmac_f32_dpp v147, v82, v106 row_shl:15 row_mask:0xf bank_mask:0xf
	v_fmac_f32_dpp v146, v83, v107 row_shl:15 row_mask:0xf bank_mask:0xf
	v_fmac_f32_dpp v214, v84, v100 row_shr:2 row_mask:0xf bank_mask:0xf
	v_fmac_f32_dpp v213, v85, v101 row_shr:2 row_mask:0xf bank_mask:0xf
	v_fmac_f32_dpp v147, v86, v102 row_shr:2 row_mask:0xf bank_mask:0xf
	v_fmac_f32_dpp v146, v87, v103 row_shr:2 row_mask:0xf bank_mask:0xf
	v_fmac_f32_dpp v214, v80, v100 row_shl:14 row_mask:0xf bank_mask:0xf
	v_fmac_f32_dpp v213, v81, v101 row_shl:14 row_mask:0xf bank_mask:0xf
	v_fmac_f32_dpp v147, v82, v102 row_shl:14 row_mask:0xf bank_mask:0xf
	v_fmac_f32_dpp v146, v83, v103 row_shl:14 row_mask:0xf bank_mask:0xf
	s_nop 0
	v_fma_f32 v84, v108, v80, v112
	v_fma_f32 v85, v109, v81, v113
	v_fma_f32 v86, v110, v82, v114
	v_fma_f32 v87, v111, v83, v115
	v_fmac_f32_dpp v84, v80, v104 row_shr:1 row_mask:0xf bank_mask:0xf
	v_fmac_f32_dpp v85, v81, v105 row_shr:1 row_mask:0xf bank_mask:0xf
	v_fmac_f32_dpp v86, v82, v106 row_shr:1 row_mask:0xf bank_mask:0xf
	v_fmac_f32_dpp v87, v83, v107 row_shr:1 row_mask:0xf bank_mask:0xf
	v_fmac_f32_dpp v84, v118, v104 row_shl:15 row_mask:0xf bank_mask:0xf
	v_fmac_f32_dpp v85, v119, v105 row_shl:15 row_mask:0xf bank_mask:0xf
	v_fmac_f32_dpp v86, v120, v106 row_shl:15 row_mask:0xf bank_mask:0xf
	v_fmac_f32_dpp v87, v121, v107 row_shl:15 row_mask:0xf bank_mask:0xf
	v_fmac_f32_dpp v84, v80, v100 row_shr:2 row_mask:0xf bank_mask:0xf
	v_fmac_f32_dpp v85, v81, v101 row_shr:2 row_mask:0xf bank_mask:0xf
	v_fmac_f32_dpp v86, v82, v102 row_shr:2 row_mask:0xf bank_mask:0xf
	v_fmac_f32_dpp v87, v83, v103 row_shr:2 row_mask:0xf bank_mask:0xf
	v_fmac_f32_dpp v84, v118, v100 row_shl:14 row_mask:0xf bank_mask:0xf
	v_fmac_f32_dpp v85, v119, v101 row_shl:14 row_mask:0xf bank_mask:0xf
	v_fmac_f32_dpp v86, v120, v102 row_shl:14 row_mask:0xf bank_mask:0xf
	v_fmac_f32_dpp v87, v121, v103 row_shl:14 row_mask:0xf bank_mask:0xf
	v_mov_b32_e32 v118, 0
	v_mov_b32_e32 v119, 0
	s_cbranch_vccnz .LBB0_752
	ds_read_b128 v[116:119], v180 offset:4096
; #define LAS __attribute__((address_space(3)))
; __device__ __forceinline__ float conv1(float cur, float prv, float w0, float w1, float w2, float b) {
;     float r, t1, t2;
;     asm volatile(
;         "s_nop 1\n\t"
;         "v_mov_b32_dpp %1, %4 row_ror:1 row_mask:0xf bank_mask:0xf\n\t"
;         "v_mov_b32_dpp %2, %4 row_ror:2 row_mask:0xf bank_mask:0xf\n\t"
;         "v_fma_f32 %0, %7, %3, %8\n\t"
;         "v_mov_b32_dpp %1, %3 row_shr:1 row_mask:0xf bank_mask:0xf\n\t"
;         "v_mov_b32_dpp %2, %3 row_shr:2 row_mask:0xf bank_mask:0xf\n\t"
;         "v_fmac_f32 %0, %6, %1\n\t"
;         "v_fmac_f32 %0, %5, %2\n\t"
;         : "=&v"(r), "=&v"(t1), "=&v"(t2) : "v"(cur), "v"(prv), "v"(w0), "v"(w1), "v"(w2), "v"(b));
;     return r;
; }
;     __device__ __forceinline__ void operator()(f32x4 (&acc)[2][2][4][2], const Unit& u, int wr, int wc, int fr, int fq, LAS unsigned char* xl) const {
;     ...
;             for (int n = 0; n < 2; ++n) {
;                 const int lc = s * 128 + chl + 4 * n;
;                 const f32x4 w0 = *(const LAS f32x4*)(wt + lc), w1 = *(const LAS f32x4*)(wt + 256 + lc), w2 = *(const LAS f32x4*)(wt + 512 + lc), bb = *(const LAS f32x4*)(wt + 768 + lc);
; #pragma unroll
;                 for (int ai = 0; ai < 2; ++ai) {
;                     const int blk = ai * 2 + wr;
;                     f32x4 pg = (f32x4){0.f, 0.f, 0.f, 0.f};
;                     if (blk > 0) pg = *(const LAS f32x4*)(bnd + (((blk - 1) * 2 + (fr & 1)) * 256 + lc));
; #pragma unroll
;                     for (int m = 3; m >= 0; --m) acc[ai][s][m][n] = conv3(acc[ai][s][m][n], m == 0 ? pg : acc[ai][s][m - 1][n], w0, w1, w2, bb);
.LBB0_752:
	v_fma_f32 v99, v108, v76, v112
	v_fma_f32 v98, v109, v77, v113
	v_fma_f32 v97, v110, v78, v114
	v_fma_f32 v96, v111, v79, v115
	v_fmac_f32_dpp v99, v76, v104 row_shr:1 row_mask:0xf bank_mask:0xf
	v_fmac_f32_dpp v98, v77, v105 row_shr:1 row_mask:0xf bank_mask:0xf
	v_fmac_f32_dpp v97, v78, v106 row_shr:1 row_mask:0xf bank_mask:0xf
	v_fmac_f32_dpp v96, v79, v107 row_shr:1 row_mask:0xf bank_mask:0xf
	v_fmac_f32_dpp v99, v72, v104 row_shl:15 row_mask:0xf bank_mask:0xf
	v_fmac_f32_dpp v98, v73, v105 row_shl:15 row_mask:0xf bank_mask:0xf
	v_fmac_f32_dpp v97, v74, v106 row_shl:15 row_mask:0xf bank_mask:0xf
	v_fmac_f32_dpp v96, v75, v107 row_shl:15 row_mask:0xf bank_mask:0xf
	v_fmac_f32_dpp v99, v76, v100 row_shr:2 row_mask:0xf bank_mask:0xf
	v_fmac_f32_dpp v98, v77, v101 row_shr:2 row_mask:0xf bank_mask:0xf
	v_fmac_f32_dpp v97, v78, v102 row_shr:2 row_mask:0xf bank_mask:0xf
	v_fmac_f32_dpp v96, v79, v103 row_shr:2 row_mask:0xf bank_mask:0xf
	v_fmac_f32_dpp v99, v72, v100 row_shl:14 row_mask:0xf bank_mask:0xf
	v_fmac_f32_dpp v98, v73, v101 row_shl:14 row_mask:0xf bank_mask:0xf
	v_fmac_f32_dpp v97, v74, v102 row_shl:14 row_mask:0xf bank_mask:0xf
	v_fmac_f32_dpp v96, v75, v103 row_shl:14 row_mask:0xf bank_mask:0xf
	s_nop 0
	v_fma_f32 v129, v108, v72, v112
	v_fma_f32 v128, v109, v73, v113
	v_fma_f32 v121, v110, v74, v114
	v_fma_f32 v120, v111, v75, v115
	v_fmac_f32_dpp v129, v72, v104 row_shr:1 row_mask:0xf bank_mask:0xf
	v_fmac_f32_dpp v128, v73, v105 row_shr:1 row_mask:0xf bank_mask:0xf
	v_fmac_f32_dpp v121, v74, v106 row_shr:1 row_mask:0xf bank_mask:0xf
	v_fmac_f32_dpp v120, v75, v107 row_shr:1 row_mask:0xf bank_mask:0xf
	v_fmac_f32_dpp v129, v68, v104 row_shl:15 row_mask:0xf bank_mask:0xf
	v_fmac_f32_dpp v128, v69, v105 row_shl:15 row_mask:0xf bank_mask:0xf
	v_fmac_f32_dpp v121, v70, v106 row_shl:15 row_mask:0xf bank_mask:0xf
	v_fmac_f32_dpp v120, v71, v107 row_shl:15 row_mask:0xf bank_mask:0xf
	v_fmac_f32_dpp v129, v72, v100 row_shr:2 row_mask:0xf bank_mask:0xf
	v_fmac_f32_dpp v128, v73, v101 row_shr:2 row_mask:0xf bank_mask:0xf
	v_fmac_f32_dpp v121, v74, v102 row_shr:2 row_mask:0xf bank_mask:0xf
	v_fmac_f32_dpp v120, v75, v103 row_shr:2 row_mask:0xf bank_mask:0xf
	v_fmac_f32_dpp v129, v68, v100 row_shl:14 row_mask:0xf bank_mask:0xf
	v_fmac_f32_dpp v128, v69, v101 row_shl:14 row_mask:0xf bank_mask:0xf
	v_fmac_f32_dpp v121, v70, v102 row_shl:14 row_mask:0xf bank_mask:0xf
	v_fmac_f32_dpp v120, v71, v103 row_shl:14 row_mask:0xf bank_mask:0xf
	s_nop 0
	v_fma_f32 v135, v108, v68, v112
	v_fma_f32 v134, v109, v69, v113
	v_fma_f32 v131, v110, v70, v114
	v_fma_f32 v130, v111, v71, v115
	v_fmac_f32_dpp v135, v68, v104 row_shr:1 row_mask:0xf bank_mask:0xf
	v_fmac_f32_dpp v134, v69, v105 row_shr:1 row_mask:0xf bank_mask:0xf
	v_fmac_f32_dpp v131, v70, v106 row_shr:1 row_mask:0xf bank_mask:0xf
	v_fmac_f32_dpp v130, v71, v107 row_shr:1 row_mask:0xf bank_mask:0xf
	v_fmac_f32_dpp v135, v64, v104 row_shl:15 row_mask:0xf bank_mask:0xf
	v_fmac_f32_dpp v134, v65, v105 row_shl:15 row_mask:0xf bank_mask:0xf
	v_fmac_f32_dpp v131, v66, v106 row_shl:15 row_mask:0xf bank_mask:0xf
	v_fmac_f32_dpp v130, v67, v107 row_shl:15 row_mask:0xf bank_mask:0xf
	v_fmac_f32_dpp v135, v68, v100 row_shr:2 row_mask:0xf bank_mask:0xf
	v_fmac_f32_dpp v134, v69, v101 row_shr:2 row_mask:0xf bank_mask:0xf
	v_fmac_f32_dpp v131, v70, v102 row_shr:2 row_mask:0xf bank_mask:0xf
	v_fmac_f32_dpp v130, v71, v103 row_shr:2 row_mask:0xf bank_mask:0xf
	v_fmac_f32_dpp v135, v64, v100 row_shl:14 row_mask:0xf bank_mask:0xf
	v_fmac_f32_dpp v134, v65, v101 row_shl:14 row_mask:0xf bank_mask:0xf
	v_fmac_f32_dpp v131, v66, v102 row_shl:14 row_mask:0xf bank_mask:0xf
	v_fmac_f32_dpp v130, v67, v103 row_shl:14 row_mask:0xf bank_mask:0xf
	s_waitcnt lgkmcnt(0)
	s_nop 0
	v_fma_f32 v140, v108, v64, v112
	s_nop 1
	v_fmac_f32_dpp v140, v64, v104 row_shr:1 row_mask:0xf bank_mask:0xf
	s_nop 1
	v_fmac_f32_dpp v140, v116, v104 row_shl:15 row_mask:0xf bank_mask:0xf
	s_nop 1
	v_fmac_f32_dpp v140, v64, v100 row_shr:2 row_mask:0xf bank_mask:0xf
	s_nop 1
	v_fmac_f32_dpp v140, v116, v100 row_shl:14 row_mask:0xf bank_mask:0xf
	s_nop 0
	v_fma_f32 v108, v109, v65, v113
	v_fma_f32 v104, v110, v66, v114
	v_fma_f32 v100, v111, v67, v115
	v_fmac_f32_dpp v108, v65, v105 row_shr:1 row_mask:0xf bank_mask:0xf
	v_fmac_f32_dpp v104, v66, v106 row_shr:1 row_mask:0xf bank_mask:0xf
	v_fmac_f32_dpp v100, v67, v107 row_shr:1 row_mask:0xf bank_mask:0xf
	v_fmac_f32_dpp v108, v117, v105 row_shl:15 row_mask:0xf bank_mask:0xf
	v_fmac_f32_dpp v104, v118, v106 row_shl:15 row_mask:0xf bank_mask:0xf
	v_fmac_f32_dpp v100, v119, v107 row_shl:15 row_mask:0xf bank_mask:0xf
	v_fmac_f32_dpp v108, v65, v101 row_shr:2 row_mask:0xf bank_mask:0xf
	v_fmac_f32_dpp v104, v66, v102 row_shr:2 row_mask:0xf bank_mask:0xf
	v_fmac_f32_dpp v100, v67, v103 row_shr:2 row_mask:0xf bank_mask:0xf
	v_fmac_f32_dpp v108, v117, v101 row_shl:14 row_mask:0xf bank_mask:0xf
	v_fmac_f32_dpp v104, v118, v102 row_shl:14 row_mask:0xf bank_mask:0xf
	v_fmac_f32_dpp v100, v119, v103 row_shl:14 row_mask:0xf bank_mask:0xf
	ds_read_b128 v[64:67], v166
	ds_read_b128 v[68:71], v167
	ds_read_b128 v[72:75], v168
	ds_read_b128 v[76:79], v169
	v_mov_b32_e32 v80, 0
	s_and_b64 vcc, exec, s[10:11]
	v_mov_b32_e32 v92, 0
	v_mov_b32_e32 v93, 0
	v_mov_b32_e32 v94, 0
	v_mov_b32_e32 v95, 0
	s_cbranch_vccnz .LBB0_754
	ds_read_b128 v[92:95], v170
; #define LAS __attribute__((address_space(3)))
; __device__ __forceinline__ float conv1(float cur, float prv, float w0, float w1, float w2, float b) {
;     float r, t1, t2;
;     asm volatile(
;         "s_nop 1\n\t"
;         "v_mov_b32_dpp %1, %4 row_ror:1 row_mask:0xf bank_mask:0xf\n\t"
;         "v_mov_b32_dpp %2, %4 row_ror:2 row_mask:0xf bank_mask:0xf\n\t"
;         "v_fma_f32 %0, %7, %3, %8\n\t"
;         "v_mov_b32_dpp %1, %3 row_shr:1 row_mask:0xf bank_mask:0xf\n\t"
;         "v_mov_b32_dpp %2, %3 row_shr:2 row_mask:0xf bank_mask:0xf\n\t"
;         "v_fmac_f32 %0, %6, %1\n\t"
;         "v_fmac_f32 %0, %5, %2\n\t"
;         : "=&v"(r), "=&v"(t1), "=&v"(t2) : "v"(cur), "v"(prv), "v"(w0), "v"(w1), "v"(w2), "v"(b));
;     return r;
; }
;     __device__ __forceinline__ void operator()(f32x4 (&acc)[2][2][4][2], const Unit& u, int wr, int wc, int fr, int fq, LAS unsigned char* xl) const {
;     ...
;             for (int n = 0; n < 2; ++n) {
;                 const int lc = s * 128 + chl + 4 * n;
;                 const f32x4 w0 = *(const LAS f32x4*)(wt + lc), w1 = *(const LAS f32x4*)(wt + 256 + lc), w2 = *(const LAS f32x4*)(wt + 512 + lc), bb = *(const LAS f32x4*)(wt + 768 + lc);
; #pragma unroll
;                 for (int ai = 0; ai < 2; ++ai) {
;                     const int blk = ai * 2 + wr;
;                     f32x4 pg = (f32x4){0.f, 0.f, 0.f, 0.f};
;                     if (blk > 0) pg = *(const LAS f32x4*)(bnd + (((blk - 1) * 2 + (fr & 1)) * 256 + lc));
; #pragma unroll
;                     for (int m = 3; m >= 0; --m) acc[ai][s][m][n] = conv3(acc[ai][s][m][n], m == 0 ? pg : acc[ai][s][m - 1][n], w0, w1, w2, bb);
.LBB0_754:
	s_waitcnt lgkmcnt(0)
	v_fma_f32 v111, v72, v60, v76
	v_fma_f32 v109, v73, v61, v77
	v_fma_f32 v107, v74, v62, v78
	v_fma_f32 v106, v75, v63, v79
	v_fmac_f32_dpp v111, v60, v68 row_shr:1 row_mask:0xf bank_mask:0xf
	v_fmac_f32_dpp v109, v61, v69 row_shr:1 row_mask:0xf bank_mask:0xf
	v_fmac_f32_dpp v107, v62, v70 row_shr:1 row_mask:0xf bank_mask:0xf
	v_fmac_f32_dpp v106, v63, v71 row_shr:1 row_mask:0xf bank_mask:0xf
	v_fmac_f32_dpp v111, v56, v68 row_shl:15 row_mask:0xf bank_mask:0xf
	v_fmac_f32_dpp v109, v57, v69 row_shl:15 row_mask:0xf bank_mask:0xf
	v_fmac_f32_dpp v107, v58, v70 row_shl:15 row_mask:0xf bank_mask:0xf
	v_fmac_f32_dpp v106, v59, v71 row_shl:15 row_mask:0xf bank_mask:0xf
	v_fmac_f32_dpp v111, v60, v64 row_shr:2 row_mask:0xf bank_mask:0xf
	v_fmac_f32_dpp v109, v61, v65 row_shr:2 row_mask:0xf bank_mask:0xf
	v_fmac_f32_dpp v107, v62, v66 row_shr:2 row_mask:0xf bank_mask:0xf
	v_fmac_f32_dpp v106, v63, v67 row_shr:2 row_mask:0xf bank_mask:0xf
	v_fmac_f32_dpp v111, v56, v64 row_shl:14 row_mask:0xf bank_mask:0xf
	v_fmac_f32_dpp v109, v57, v65 row_shl:14 row_mask:0xf bank_mask:0xf
	v_fmac_f32_dpp v107, v58, v66 row_shl:14 row_mask:0xf bank_mask:0xf
	v_fmac_f32_dpp v106, v59, v67 row_shl:14 row_mask:0xf bank_mask:0xf
	s_and_b64 vcc, exec, s[8:9]
	v_mov_b32_e32 v82, 0
	v_mov_b32_e32 v81, 0
	v_mov_b32_e32 v83, 0
	v_fma_f32 v115, v72, v56, v76
	v_fma_f32 v114, v73, v57, v77
	v_fma_f32 v113, v74, v58, v78
	v_fma_f32 v112, v75, v59, v79
	v_fmac_f32_dpp v115, v56, v68 row_shr:1 row_mask:0xf bank_mask:0xf
	v_fmac_f32_dpp v114, v57, v69 row_shr:1 row_mask:0xf bank_mask:0xf
	v_fmac_f32_dpp v113, v58, v70 row_shr:1 row_mask:0xf bank_mask:0xf
	v_fmac_f32_dpp v112, v59, v71 row_shr:1 row_mask:0xf bank_mask:0xf
	v_fmac_f32_dpp v115, v52, v68 row_shl:15 row_mask:0xf bank_mask:0xf
	v_fmac_f32_dpp v114, v53, v69 row_shl:15 row_mask:0xf bank_mask:0xf
	v_fmac_f32_dpp v113, v54, v70 row_shl:15 row_mask:0xf bank_mask:0xf
	v_fmac_f32_dpp v112, v55, v71 row_shl:15 row_mask:0xf bank_mask:0xf
	v_fmac_f32_dpp v115, v56, v64 row_shr:2 row_mask:0xf bank_mask:0xf
	v_fmac_f32_dpp v114, v57, v65 row_shr:2 row_mask:0xf bank_mask:0xf
	v_fmac_f32_dpp v113, v58, v66 row_shr:2 row_mask:0xf bank_mask:0xf
	v_fmac_f32_dpp v112, v59, v67 row_shr:2 row_mask:0xf bank_mask:0xf
	v_fmac_f32_dpp v115, v52, v64 row_shl:14 row_mask:0xf bank_mask:0xf
	v_fmac_f32_dpp v114, v53, v65 row_shl:14 row_mask:0xf bank_mask:0xf
	v_fmac_f32_dpp v113, v54, v66 row_shl:14 row_mask:0xf bank_mask:0xf
	v_fmac_f32_dpp v112, v55, v67 row_shl:14 row_mask:0xf bank_mask:0xf
	s_nop 0
	v_fma_f32 v119, v72, v52, v76
	v_fma_f32 v118, v73, v53, v77
	v_fma_f32 v117, v74, v54, v78
	v_fma_f32 v116, v75, v55, v79
	v_fmac_f32_dpp v119, v52, v68 row_shr:1 row_mask:0xf bank_mask:0xf
	v_fmac_f32_dpp v118, v53, v69 row_shr:1 row_mask:0xf bank_mask:0xf
	v_fmac_f32_dpp v117, v54, v70 row_shr:1 row_mask:0xf bank_mask:0xf
	v_fmac_f32_dpp v116, v55, v71 row_shr:1 row_mask:0xf bank_mask:0xf
	v_fmac_f32_dpp v119, v48, v68 row_shl:15 row_mask:0xf bank_mask:0xf
	v_fmac_f32_dpp v118, v49, v69 row_shl:15 row_mask:0xf bank_mask:0xf
	v_fmac_f32_dpp v117, v50, v70 row_shl:15 row_mask:0xf bank_mask:0xf
	v_fmac_f32_dpp v116, v51, v71 row_shl:15 row_mask:0xf bank_mask:0xf
	v_fmac_f32_dpp v119, v52, v64 row_shr:2 row_mask:0xf bank_mask:0xf
	v_fmac_f32_dpp v118, v53, v65 row_shr:2 row_mask:0xf bank_mask:0xf
	v_fmac_f32_dpp v117, v54, v66 row_shr:2 row_mask:0xf bank_mask:0xf
	v_fmac_f32_dpp v116, v55, v67 row_shr:2 row_mask:0xf bank_mask:0xf
	v_fmac_f32_dpp v119, v48, v64 row_shl:14 row_mask:0xf bank_mask:0xf
	v_fmac_f32_dpp v118, v49, v65 row_shl:14 row_mask:0xf bank_mask:0xf
	v_fmac_f32_dpp v117, v50, v66 row_shl:14 row_mask:0xf bank_mask:0xf
	v_fmac_f32_dpp v116, v51, v67 row_shl:14 row_mask:0xf bank_mask:0xf
	s_nop 0
	v_fma_f32 v52, v72, v48, v76
	v_fma_f32 v53, v73, v49, v77
	v_fma_f32 v54, v74, v50, v78
	v_fma_f32 v55, v75, v51, v79
	v_fmac_f32_dpp v52, v48, v68 row_shr:1 row_mask:0xf bank_mask:0xf
	v_fmac_f32_dpp v53, v49, v69 row_shr:1 row_mask:0xf bank_mask:0xf
	v_fmac_f32_dpp v54, v50, v70 row_shr:1 row_mask:0xf bank_mask:0xf
	v_fmac_f32_dpp v55, v51, v71 row_shr:1 row_mask:0xf bank_mask:0xf
	v_fmac_f32_dpp v52, v92, v68 row_shl:15 row_mask:0xf bank_mask:0xf
	v_fmac_f32_dpp v53, v93, v69 row_shl:15 row_mask:0xf bank_mask:0xf
	v_fmac_f32_dpp v54, v94, v70 row_shl:15 row_mask:0xf bank_mask:0xf
	v_fmac_f32_dpp v55, v95, v71 row_shl:15 row_mask:0xf bank_mask:0xf
	v_fmac_f32_dpp v52, v48, v64 row_shr:2 row_mask:0xf bank_mask:0xf
	v_fmac_f32_dpp v53, v49, v65 row_shr:2 row_mask:0xf bank_mask:0xf
	v_fmac_f32_dpp v54, v50, v66 row_shr:2 row_mask:0xf bank_mask:0xf
	v_fmac_f32_dpp v55, v51, v67 row_shr:2 row_mask:0xf bank_mask:0xf
	v_fmac_f32_dpp v52, v92, v64 row_shl:14 row_mask:0xf bank_mask:0xf
	v_fmac_f32_dpp v53, v93, v65 row_shl:14 row_mask:0xf bank_mask:0xf
	v_fmac_f32_dpp v54, v94, v66 row_shl:14 row_mask:0xf bank_mask:0xf
	v_fmac_f32_dpp v55, v95, v67 row_shl:14 row_mask:0xf bank_mask:0xf
	s_cbranch_vccnz .LBB0_756
	ds_read_b128 v[80:83], v181 offset:4096
; #define LAS __attribute__((address_space(3)))
; __device__ __forceinline__ float conv1(float cur, float prv, float w0, float w1, float w2, float b) {
;     float r, t1, t2;
;     asm volatile(
;         "s_nop 1\n\t"
;         "v_mov_b32_dpp %1, %4 row_ror:1 row_mask:0xf bank_mask:0xf\n\t"
;         "v_mov_b32_dpp %2, %4 row_ror:2 row_mask:0xf bank_mask:0xf\n\t"
;         "v_fma_f32 %0, %7, %3, %8\n\t"
;         "v_mov_b32_dpp %1, %3 row_shr:1 row_mask:0xf bank_mask:0xf\n\t"
;         "v_mov_b32_dpp %2, %3 row_shr:2 row_mask:0xf bank_mask:0xf\n\t"
;         "v_fmac_f32 %0, %6, %1\n\t"
;         "v_fmac_f32 %0, %5, %2\n\t"
;         : "=&v"(r), "=&v"(t1), "=&v"(t2) : "v"(cur), "v"(prv), "v"(w0), "v"(w1), "v"(w2), "v"(b));
;     return r;
; }
;     __device__ __forceinline__ void operator()(f32x4 (&acc)[2][2][4][2], const Unit& u, int wr, int wc, int fr, int fq, LAS unsigned char* xl) const {
;     ...
;             for (int n = 0; n < 2; ++n) {
;                 const int lc = s * 128 + chl + 4 * n;
;                 const f32x4 w0 = *(const LAS f32x4*)(wt + lc), w1 = *(const LAS f32x4*)(wt + 256 + lc), w2 = *(const LAS f32x4*)(wt + 512 + lc), bb = *(const LAS f32x4*)(wt + 768 + lc);
; #pragma unroll
;                 for (int ai = 0; ai < 2; ++ai) {
;                     const int blk = ai * 2 + wr;
;                     f32x4 pg = (f32x4){0.f, 0.f, 0.f, 0.f};
;                     if (blk > 0) pg = *(const LAS f32x4*)(bnd + (((blk - 1) * 2 + (fr & 1)) * 256 + lc));
; #pragma unroll
;                     for (int m = 3; m >= 0; --m) acc[ai][s][m][n] = conv3(acc[ai][s][m][n], m == 0 ? pg : acc[ai][s][m - 1][n], w0, w1, w2, bb);
.LBB0_756:
	v_fma_f32 v63, v72, v44, v76
	v_fma_f32 v62, v73, v45, v77
	v_fma_f32 v61, v74, v46, v78
	v_fma_f32 v60, v75, v47, v79
	v_fmac_f32_dpp v63, v44, v68 row_shr:1 row_mask:0xf bank_mask:0xf
	v_fmac_f32_dpp v62, v45, v69 row_shr:1 row_mask:0xf bank_mask:0xf
	v_fmac_f32_dpp v61, v46, v70 row_shr:1 row_mask:0xf bank_mask:0xf
	v_fmac_f32_dpp v60, v47, v71 row_shr:1 row_mask:0xf bank_mask:0xf
	v_fmac_f32_dpp v63, v40, v68 row_shl:15 row_mask:0xf bank_mask:0xf
	v_fmac_f32_dpp v62, v41, v69 row_shl:15 row_mask:0xf bank_mask:0xf
	v_fmac_f32_dpp v61, v42, v70 row_shl:15 row_mask:0xf bank_mask:0xf
	v_fmac_f32_dpp v60, v43, v71 row_shl:15 row_mask:0xf bank_mask:0xf
	v_fmac_f32_dpp v63, v44, v64 row_shr:2 row_mask:0xf bank_mask:0xf
	v_fmac_f32_dpp v62, v45, v65 row_shr:2 row_mask:0xf bank_mask:0xf
	v_fmac_f32_dpp v61, v46, v66 row_shr:2 row_mask:0xf bank_mask:0xf
	v_fmac_f32_dpp v60, v47, v67 row_shr:2 row_mask:0xf bank_mask:0xf
	v_fmac_f32_dpp v63, v40, v64 row_shl:14 row_mask:0xf bank_mask:0xf
	v_fmac_f32_dpp v62, v41, v65 row_shl:14 row_mask:0xf bank_mask:0xf
	v_fmac_f32_dpp v61, v42, v66 row_shl:14 row_mask:0xf bank_mask:0xf
	v_fmac_f32_dpp v60, v43, v67 row_shl:14 row_mask:0xf bank_mask:0xf
	s_nop 0
	v_fma_f32 v95, v72, v40, v76
	v_fma_f32 v94, v73, v41, v77
	v_fma_f32 v93, v74, v42, v78
	v_fma_f32 v92, v75, v43, v79
	v_fmac_f32_dpp v95, v40, v68 row_shr:1 row_mask:0xf bank_mask:0xf
	v_fmac_f32_dpp v94, v41, v69 row_shr:1 row_mask:0xf bank_mask:0xf
	v_fmac_f32_dpp v93, v42, v70 row_shr:1 row_mask:0xf bank_mask:0xf
	v_fmac_f32_dpp v92, v43, v71 row_shr:1 row_mask:0xf bank_mask:0xf
	v_fmac_f32_dpp v95, v36, v68 row_shl:15 row_mask:0xf bank_mask:0xf
	v_fmac_f32_dpp v94, v37, v69 row_shl:15 row_mask:0xf bank_mask:0xf
	v_fmac_f32_dpp v93, v38, v70 row_shl:15 row_mask:0xf bank_mask:0xf
	v_fmac_f32_dpp v92, v39, v71 row_shl:15 row_mask:0xf bank_mask:0xf
	v_fmac_f32_dpp v95, v40, v64 row_shr:2 row_mask:0xf bank_mask:0xf
	v_fmac_f32_dpp v94, v41, v65 row_shr:2 row_mask:0xf bank_mask:0xf
	v_fmac_f32_dpp v93, v42, v66 row_shr:2 row_mask:0xf bank_mask:0xf
	v_fmac_f32_dpp v92, v43, v67 row_shr:2 row_mask:0xf bank_mask:0xf
	v_fmac_f32_dpp v95, v36, v64 row_shl:14 row_mask:0xf bank_mask:0xf
	v_fmac_f32_dpp v94, v37, v65 row_shl:14 row_mask:0xf bank_mask:0xf
	v_fmac_f32_dpp v93, v38, v66 row_shl:14 row_mask:0xf bank_mask:0xf
	v_fmac_f32_dpp v92, v39, v67 row_shl:14 row_mask:0xf bank_mask:0xf
	s_nop 0
	v_fma_f32 v105, v72, v36, v76
	v_fma_f32 v103, v73, v37, v77
	v_fma_f32 v102, v74, v38, v78
	v_fma_f32 v101, v75, v39, v79
	v_fmac_f32_dpp v105, v36, v68 row_shr:1 row_mask:0xf bank_mask:0xf
	v_fmac_f32_dpp v103, v37, v69 row_shr:1 row_mask:0xf bank_mask:0xf
	v_fmac_f32_dpp v102, v38, v70 row_shr:1 row_mask:0xf bank_mask:0xf
	v_fmac_f32_dpp v101, v39, v71 row_shr:1 row_mask:0xf bank_mask:0xf
	v_fmac_f32_dpp v105, v32, v68 row_shl:15 row_mask:0xf bank_mask:0xf
	v_fmac_f32_dpp v103, v33, v69 row_shl:15 row_mask:0xf bank_mask:0xf
	v_fmac_f32_dpp v102, v34, v70 row_shl:15 row_mask:0xf bank_mask:0xf
	v_fmac_f32_dpp v101, v35, v71 row_shl:15 row_mask:0xf bank_mask:0xf
	v_fmac_f32_dpp v105, v36, v64 row_shr:2 row_mask:0xf bank_mask:0xf
	v_fmac_f32_dpp v103, v37, v65 row_shr:2 row_mask:0xf bank_mask:0xf
	v_fmac_f32_dpp v102, v38, v66 row_shr:2 row_mask:0xf bank_mask:0xf
	v_fmac_f32_dpp v101, v39, v67 row_shr:2 row_mask:0xf bank_mask:0xf
	v_fmac_f32_dpp v105, v32, v64 row_shl:14 row_mask:0xf bank_mask:0xf
	v_fmac_f32_dpp v103, v33, v65 row_shl:14 row_mask:0xf bank_mask:0xf
	v_fmac_f32_dpp v102, v34, v66 row_shl:14 row_mask:0xf bank_mask:0xf
	v_fmac_f32_dpp v101, v35, v67 row_shl:14 row_mask:0xf bank_mask:0xf
	s_waitcnt lgkmcnt(0)
	s_nop 0
	v_fma_f32 v110, v72, v32, v76
	s_nop 1
	v_fmac_f32_dpp v110, v32, v68 row_shr:1 row_mask:0xf bank_mask:0xf
	s_nop 1
	v_fmac_f32_dpp v110, v80, v68 row_shl:15 row_mask:0xf bank_mask:0xf
	s_nop 1
	v_fmac_f32_dpp v110, v32, v64 row_shr:2 row_mask:0xf bank_mask:0xf
	s_nop 1
	v_fmac_f32_dpp v110, v80, v64 row_shl:14 row_mask:0xf bank_mask:0xf
	s_nop 0
	s_nop 0
	v_fma_f32 v68, v73, v33, v77
	s_nop 1
	v_fmac_f32_dpp v68, v33, v69 row_shr:1 row_mask:0xf bank_mask:0xf
	s_nop 1
	v_fmac_f32_dpp v68, v81, v69 row_shl:15 row_mask:0xf bank_mask:0xf
	s_nop 1
	v_fmac_f32_dpp v68, v33, v65 row_shr:2 row_mask:0xf bank_mask:0xf
	s_nop 1
	v_fmac_f32_dpp v68, v81, v65 row_shl:14 row_mask:0xf bank_mask:0xf
	s_nop 0
	v_fma_f32 v65, v74, v34, v78
	v_fma_f32 v64, v75, v35, v79
	s_nop 0
	v_fmac_f32_dpp v65, v34, v70 row_shr:1 row_mask:0xf bank_mask:0xf
	v_fmac_f32_dpp v64, v35, v71 row_shr:1 row_mask:0xf bank_mask:0xf
	s_nop 0
	v_fmac_f32_dpp v65, v82, v70 row_shl:15 row_mask:0xf bank_mask:0xf
	v_fmac_f32_dpp v64, v83, v71 row_shl:15 row_mask:0xf bank_mask:0xf
	s_nop 0
	v_fmac_f32_dpp v65, v34, v66 row_shr:2 row_mask:0xf bank_mask:0xf
	v_fmac_f32_dpp v64, v35, v67 row_shr:2 row_mask:0xf bank_mask:0xf
	s_nop 0
	v_fmac_f32_dpp v65, v82, v66 row_shl:14 row_mask:0xf bank_mask:0xf
	v_fmac_f32_dpp v64, v83, v67 row_shl:14 row_mask:0xf bank_mask:0xf
	ds_read_b128 v[32:35], v171
	ds_read_b128 v[36:39], v172
	ds_read_b128 v[40:43], v173
	ds_read_b128 v[44:47], v174
	v_mov_b32_e32 v48, 0
	s_and_b64 vcc, exec, s[10:11]
	v_mov_b32_e32 v56, 0
	v_mov_b32_e32 v57, 0
	v_mov_b32_e32 v58, 0
	v_mov_b32_e32 v59, 0
	s_cbranch_vccnz .LBB0_758
	ds_read_b128 v[56:59], v175
; #define LAS __attribute__((address_space(3)))
; __device__ __forceinline__ float conv1(float cur, float prv, float w0, float w1, float w2, float b) {
;     float r, t1, t2;
;     asm volatile(
;         "s_nop 1\n\t"
;         "v_mov_b32_dpp %1, %4 row_ror:1 row_mask:0xf bank_mask:0xf\n\t"
;         "v_mov_b32_dpp %2, %4 row_ror:2 row_mask:0xf bank_mask:0xf\n\t"
;         "v_fma_f32 %0, %7, %3, %8\n\t"
;         "v_mov_b32_dpp %1, %3 row_shr:1 row_mask:0xf bank_mask:0xf\n\t"
;         "v_mov_b32_dpp %2, %3 row_shr:2 row_mask:0xf bank_mask:0xf\n\t"
;         "v_fmac_f32 %0, %6, %1\n\t"
;         "v_fmac_f32 %0, %5, %2\n\t"
;         : "=&v"(r), "=&v"(t1), "=&v"(t2) : "v"(cur), "v"(prv), "v"(w0), "v"(w1), "v"(w2), "v"(b));
;     return r;
; }
;     __device__ __forceinline__ void operator()(f32x4 (&acc)[2][2][4][2], const Unit& u, int wr, int wc, int fr, int fq, LAS unsigned char* xl) const {
;     ...
;             for (int n = 0; n < 2; ++n) {
;                 const int lc = s * 128 + chl + 4 * n;
;                 const f32x4 w0 = *(const LAS f32x4*)(wt + lc), w1 = *(const LAS f32x4*)(wt + 256 + lc), w2 = *(const LAS f32x4*)(wt + 512 + lc), bb = *(const LAS f32x4*)(wt + 768 + lc);
; #pragma unroll
;                 for (int ai = 0; ai < 2; ++ai) {
;                     const int blk = ai * 2 + wr;
;                     f32x4 pg = (f32x4){0.f, 0.f, 0.f, 0.f};
;                     if (blk > 0) pg = *(const LAS f32x4*)(bnd + (((blk - 1) * 2 + (fr & 1)) * 256 + lc));
; #pragma unroll
;                     for (int m = 3; m >= 0; --m) acc[ai][s][m][n] = conv3(acc[ai][s][m][n], m == 0 ? pg : acc[ai][s][m - 1][n], w0, w1, w2, bb);
.LBB0_758:
	s_waitcnt lgkmcnt(0)
	v_fma_f32 v67, v40, v28, v44
	v_fma_f32 v66, v41, v29, v45
	s_nop 0
	v_fmac_f32_dpp v67, v28, v36 row_shr:1 row_mask:0xf bank_mask:0xf
	v_fmac_f32_dpp v66, v29, v37 row_shr:1 row_mask:0xf bank_mask:0xf
	s_nop 0
	v_fmac_f32_dpp v67, v24, v36 row_shl:15 row_mask:0xf bank_mask:0xf
	v_fmac_f32_dpp v66, v25, v37 row_shl:15 row_mask:0xf bank_mask:0xf
	s_nop 0
	v_fmac_f32_dpp v67, v28, v32 row_shr:2 row_mask:0xf bank_mask:0xf
	v_fmac_f32_dpp v66, v29, v33 row_shr:2 row_mask:0xf bank_mask:0xf
	s_nop 0
	v_fmac_f32_dpp v67, v24, v32 row_shl:14 row_mask:0xf bank_mask:0xf
	v_fmac_f32_dpp v66, v25, v33 row_shl:14 row_mask:0xf bank_mask:0xf
	s_and_b64 vcc, exec, s[8:9]
	v_mov_b32_e32 v50, 0
	v_fma_f32 v29, v42, v30, v46
	v_fma_f32 v28, v43, v31, v47
	s_nop 0
	v_fmac_f32_dpp v29, v30, v38 row_shr:1 row_mask:0xf bank_mask:0xf
	v_fmac_f32_dpp v28, v31, v39 row_shr:1 row_mask:0xf bank_mask:0xf
	s_nop 0
	v_fmac_f32_dpp v29, v26, v38 row_shl:15 row_mask:0xf bank_mask:0xf
	v_fmac_f32_dpp v28, v27, v39 row_shl:15 row_mask:0xf bank_mask:0xf
	s_nop 0
	v_fmac_f32_dpp v29, v30, v34 row_shr:2 row_mask:0xf bank_mask:0xf
	v_fmac_f32_dpp v28, v31, v35 row_shr:2 row_mask:0xf bank_mask:0xf
	s_nop 0
	v_fmac_f32_dpp v29, v26, v34 row_shl:14 row_mask:0xf bank_mask:0xf
	v_fmac_f32_dpp v28, v27, v35 row_shl:14 row_mask:0xf bank_mask:0xf
	v_mov_b32_e32 v51, 0
	s_nop 0
	v_fma_f32 v31, v40, v24, v44
	v_fma_f32 v30, v41, v25, v45
	s_nop 0
	v_fmac_f32_dpp v31, v24, v36 row_shr:1 row_mask:0xf bank_mask:0xf
	v_fmac_f32_dpp v30, v25, v37 row_shr:1 row_mask:0xf bank_mask:0xf
	s_nop 0
	v_fmac_f32_dpp v31, v20, v36 row_shl:15 row_mask:0xf bank_mask:0xf
	v_fmac_f32_dpp v30, v21, v37 row_shl:15 row_mask:0xf bank_mask:0xf
	s_nop 0
	v_fmac_f32_dpp v31, v24, v32 row_shr:2 row_mask:0xf bank_mask:0xf
	v_fmac_f32_dpp v30, v25, v33 row_shr:2 row_mask:0xf bank_mask:0xf
	s_nop 0
	v_fmac_f32_dpp v31, v20, v32 row_shl:14 row_mask:0xf bank_mask:0xf
	v_fmac_f32_dpp v30, v21, v33 row_shl:14 row_mask:0xf bank_mask:0xf
	s_nop 0
	v_fma_f32 v25, v42, v26, v46
	v_fma_f32 v24, v43, v27, v47
	v_fma_f32 v70, v40, v20, v44
	v_fma_f32 v69, v41, v21, v45
	v_fmac_f32_dpp v25, v26, v38 row_shr:1 row_mask:0xf bank_mask:0xf
	v_fmac_f32_dpp v24, v27, v39 row_shr:1 row_mask:0xf bank_mask:0xf
	v_fmac_f32_dpp v70, v20, v36 row_shr:1 row_mask:0xf bank_mask:0xf
	v_fmac_f32_dpp v69, v21, v37 row_shr:1 row_mask:0xf bank_mask:0xf
	v_fmac_f32_dpp v25, v22, v38 row_shl:15 row_mask:0xf bank_mask:0xf
	v_fmac_f32_dpp v24, v23, v39 row_shl:15 row_mask:0xf bank_mask:0xf
	v_fmac_f32_dpp v70, v16, v36 row_shl:15 row_mask:0xf bank_mask:0xf
	v_fmac_f32_dpp v69, v17, v37 row_shl:15 row_mask:0xf bank_mask:0xf
	v_fmac_f32_dpp v25, v26, v34 row_shr:2 row_mask:0xf bank_mask:0xf
	v_fmac_f32_dpp v24, v27, v35 row_shr:2 row_mask:0xf bank_mask:0xf
	v_fmac_f32_dpp v70, v20, v32 row_shr:2 row_mask:0xf bank_mask:0xf
	v_fmac_f32_dpp v69, v21, v33 row_shr:2 row_mask:0xf bank_mask:0xf
	v_fmac_f32_dpp v25, v22, v34 row_shl:14 row_mask:0xf bank_mask:0xf
	v_fmac_f32_dpp v24, v23, v35 row_shl:14 row_mask:0xf bank_mask:0xf
	v_fmac_f32_dpp v70, v16, v32 row_shl:14 row_mask:0xf bank_mask:0xf
	v_fmac_f32_dpp v69, v17, v33 row_shl:14 row_mask:0xf bank_mask:0xf
	v_mov_b32_e32 v49, 0
	s_nop 0
	v_fma_f32 v27, v42, v22, v46
	v_fma_f32 v26, v43, v23, v47
	v_fma_f32 v20, v40, v16, v44
	v_fma_f32 v21, v41, v17, v45
	v_fmac_f32_dpp v27, v22, v38 row_shr:1 row_mask:0xf bank_mask:0xf
	v_fmac_f32_dpp v26, v23, v39 row_shr:1 row_mask:0xf bank_mask:0xf
	v_fmac_f32_dpp v20, v16, v36 row_shr:1 row_mask:0xf bank_mask:0xf
	v_fmac_f32_dpp v21, v17, v37 row_shr:1 row_mask:0xf bank_mask:0xf
	v_fmac_f32_dpp v27, v18, v38 row_shl:15 row_mask:0xf bank_mask:0xf
	v_fmac_f32_dpp v26, v19, v39 row_shl:15 row_mask:0xf bank_mask:0xf
	v_fmac_f32_dpp v20, v56, v36 row_shl:15 row_mask:0xf bank_mask:0xf
	v_fmac_f32_dpp v21, v57, v37 row_shl:15 row_mask:0xf bank_mask:0xf
	v_fmac_f32_dpp v27, v22, v34 row_shr:2 row_mask:0xf bank_mask:0xf
	v_fmac_f32_dpp v26, v23, v35 row_shr:2 row_mask:0xf bank_mask:0xf
	v_fmac_f32_dpp v20, v16, v32 row_shr:2 row_mask:0xf bank_mask:0xf
	v_fmac_f32_dpp v21, v17, v33 row_shr:2 row_mask:0xf bank_mask:0xf
	v_fmac_f32_dpp v27, v18, v34 row_shl:14 row_mask:0xf bank_mask:0xf
	v_fmac_f32_dpp v26, v19, v35 row_shl:14 row_mask:0xf bank_mask:0xf
	v_fmac_f32_dpp v20, v56, v32 row_shl:14 row_mask:0xf bank_mask:0xf
	v_fmac_f32_dpp v21, v57, v33 row_shl:14 row_mask:0xf bank_mask:0xf
	s_nop 0
	v_fma_f32 v22, v42, v18, v46
	v_fma_f32 v23, v43, v19, v47
	s_nop 0
	v_fmac_f32_dpp v22, v18, v38 row_shr:1 row_mask:0xf bank_mask:0xf
	v_fmac_f32_dpp v23, v19, v39 row_shr:1 row_mask:0xf bank_mask:0xf
	s_nop 0
	v_fmac_f32_dpp v22, v58, v38 row_shl:15 row_mask:0xf bank_mask:0xf
	v_fmac_f32_dpp v23, v59, v39 row_shl:15 row_mask:0xf bank_mask:0xf
	s_nop 0
	v_fmac_f32_dpp v22, v18, v34 row_shr:2 row_mask:0xf bank_mask:0xf
	v_fmac_f32_dpp v23, v19, v35 row_shr:2 row_mask:0xf bank_mask:0xf
	s_nop 0
	v_fmac_f32_dpp v22, v58, v34 row_shl:14 row_mask:0xf bank_mask:0xf
	v_fmac_f32_dpp v23, v59, v35 row_shl:14 row_mask:0xf bank_mask:0xf
	s_cbranch_vccnz .LBB0_760
	ds_read_b128 v[48:51], v182 offset:4096
; #define LAS __attribute__((address_space(3)))
; __device__ __forceinline__ float conv1(float cur, float prv, float w0, float w1, float w2, float b) {
;     float r, t1, t2;
;     asm volatile(
;         "s_nop 1\n\t"
;         "v_mov_b32_dpp %1, %4 row_ror:1 row_mask:0xf bank_mask:0xf\n\t"
;         "v_mov_b32_dpp %2, %4 row_ror:2 row_mask:0xf bank_mask:0xf\n\t"
;         "v_fma_f32 %0, %7, %3, %8\n\t"
;         "v_mov_b32_dpp %1, %3 row_shr:1 row_mask:0xf bank_mask:0xf\n\t"
;         "v_mov_b32_dpp %2, %3 row_shr:2 row_mask:0xf bank_mask:0xf\n\t"
;         "v_fmac_f32 %0, %6, %1\n\t"
;         "v_fmac_f32 %0, %5, %2\n\t"
;         : "=&v"(r), "=&v"(t1), "=&v"(t2) : "v"(cur), "v"(prv), "v"(w0), "v"(w1), "v"(w2), "v"(b));
;     return r;
; }
; __device__ __forceinline__ f32x4 conv3(const f32x4 cur, const f32x4 prv, const f32x4 w0, const f32x4 w1, const f32x4 w2, const f32x4 bb) {
;     f32x4 r;
; #pragma unroll
;     for (int j = 0; j < 4; ++j) r[j] = conv1(cur[j], prv[j], w0[j], w1[j], w2[j], bb[j]);
;     return r;
; }
;     __device__ __forceinline__ void operator()(f32x4 (&acc)[2][2][4][2], const Unit& u, int wr, int wc, int fr, int fq, LAS unsigned char* xl) const {
;     ...
;             for (int n = 0; n < 2; ++n) {
;                 const int lc = s * 128 + chl + 4 * n;
;                 const f32x4 w0 = *(const LAS f32x4*)(wt + lc), w1 = *(const LAS f32x4*)(wt + 256 + lc), w2 = *(const LAS f32x4*)(wt + 512 + lc), bb = *(const LAS f32x4*)(wt + 768 + lc);
; #pragma unroll
;                 for (int ai = 0; ai < 2; ++ai) {
;                     const int blk = ai * 2 + wr;
;                     f32x4 pg = (f32x4){0.f, 0.f, 0.f, 0.f};
;                     if (blk > 0) pg = *(const LAS f32x4*)(bnd + (((blk - 1) * 2 + (fr & 1)) * 256 + lc));
; #pragma unroll
;                     for (int m = 3; m >= 0; --m) acc[ai][s][m][n] = conv3(acc[ai][s][m][n], m == 0 ? pg : acc[ai][s][m - 1][n], w0, w1, w2, bb);
;                 }
;                 __builtin_amdgcn_sched_barrier(0);
;             }
;         if (wr == 0 && fr < 2) {
; #pragma unroll
;             for (int s = 0; s < NS; ++s)
; #pragma unroll
;                 for (int n = 0; n < 2; ++n) *(f32x4*)(PART + (size_t)(u.pm * 2 + fr) * C + (s ? voff : 0) + ch0 + 4 * n) = acc[0][s][0][n];
;         }
.LBB0_760:
	v_fma_f32 v17, v40, v12, v44
	v_fma_f32 v16, v41, v13, v45
	s_nop 0
	v_fmac_f32_dpp v17, v12, v36 row_shr:1 row_mask:0xf bank_mask:0xf
	v_fmac_f32_dpp v16, v13, v37 row_shr:1 row_mask:0xf bank_mask:0xf
	s_nop 0
	v_fmac_f32_dpp v17, v8, v36 row_shl:15 row_mask:0xf bank_mask:0xf
	v_fmac_f32_dpp v16, v9, v37 row_shl:15 row_mask:0xf bank_mask:0xf
	s_nop 0
	v_fmac_f32_dpp v17, v12, v32 row_shr:2 row_mask:0xf bank_mask:0xf
	v_fmac_f32_dpp v16, v13, v33 row_shr:2 row_mask:0xf bank_mask:0xf
	s_nop 0
	v_fmac_f32_dpp v17, v8, v32 row_shl:14 row_mask:0xf bank_mask:0xf
	v_fmac_f32_dpp v16, v9, v33 row_shl:14 row_mask:0xf bank_mask:0xf
	s_nop 0
	v_fma_f32 v13, v42, v14, v46
	v_fma_f32 v12, v43, v15, v47
	s_nop 0
	v_fmac_f32_dpp v13, v14, v38 row_shr:1 row_mask:0xf bank_mask:0xf
	v_fmac_f32_dpp v12, v15, v39 row_shr:1 row_mask:0xf bank_mask:0xf
	s_nop 0
	v_fmac_f32_dpp v13, v10, v38 row_shl:15 row_mask:0xf bank_mask:0xf
	v_fmac_f32_dpp v12, v11, v39 row_shl:15 row_mask:0xf bank_mask:0xf
	s_nop 0
	v_fmac_f32_dpp v13, v14, v34 row_shr:2 row_mask:0xf bank_mask:0xf
	v_fmac_f32_dpp v12, v15, v35 row_shr:2 row_mask:0xf bank_mask:0xf
	s_nop 0
	v_fmac_f32_dpp v13, v10, v34 row_shl:14 row_mask:0xf bank_mask:0xf
	v_fmac_f32_dpp v12, v11, v35 row_shl:14 row_mask:0xf bank_mask:0xf
	s_nop 0
	v_fma_f32 v15, v40, v8, v44
	v_fma_f32 v14, v41, v9, v45
	s_nop 0
	v_fmac_f32_dpp v15, v8, v36 row_shr:1 row_mask:0xf bank_mask:0xf
	v_fmac_f32_dpp v14, v9, v37 row_shr:1 row_mask:0xf bank_mask:0xf
	s_nop 0
	v_fmac_f32_dpp v15, v4, v36 row_shl:15 row_mask:0xf bank_mask:0xf
	v_fmac_f32_dpp v14, v5, v37 row_shl:15 row_mask:0xf bank_mask:0xf
	s_nop 0
	v_fmac_f32_dpp v15, v8, v32 row_shr:2 row_mask:0xf bank_mask:0xf
	v_fmac_f32_dpp v14, v9, v33 row_shr:2 row_mask:0xf bank_mask:0xf
	s_nop 0
	v_fmac_f32_dpp v15, v4, v32 row_shl:14 row_mask:0xf bank_mask:0xf
	v_fmac_f32_dpp v14, v5, v33 row_shl:14 row_mask:0xf bank_mask:0xf
	s_nop 0
	v_fma_f32 v9, v42, v10, v46
	v_fma_f32 v8, v43, v11, v47
	s_nop 0
	v_fmac_f32_dpp v9, v10, v38 row_shr:1 row_mask:0xf bank_mask:0xf
	v_fmac_f32_dpp v8, v11, v39 row_shr:1 row_mask:0xf bank_mask:0xf
	s_nop 0
	v_fmac_f32_dpp v9, v6, v38 row_shl:15 row_mask:0xf bank_mask:0xf
	v_fmac_f32_dpp v8, v7, v39 row_shl:15 row_mask:0xf bank_mask:0xf
	s_nop 0
	v_fmac_f32_dpp v9, v10, v34 row_shr:2 row_mask:0xf bank_mask:0xf
	v_fmac_f32_dpp v8, v11, v35 row_shr:2 row_mask:0xf bank_mask:0xf
	s_nop 0
	v_fmac_f32_dpp v9, v6, v34 row_shl:14 row_mask:0xf bank_mask:0xf
	v_fmac_f32_dpp v8, v7, v35 row_shl:14 row_mask:0xf bank_mask:0xf
	s_nop 0
	v_fma_f32 v11, v40, v4, v44
	v_fma_f32 v10, v41, v5, v45
	s_nop 0
	v_fmac_f32_dpp v11, v4, v36 row_shr:1 row_mask:0xf bank_mask:0xf
	v_fmac_f32_dpp v10, v5, v37 row_shr:1 row_mask:0xf bank_mask:0xf
	s_nop 0
	v_fmac_f32_dpp v11, v0, v36 row_shl:15 row_mask:0xf bank_mask:0xf
	v_fmac_f32_dpp v10, v1, v37 row_shl:15 row_mask:0xf bank_mask:0xf
	s_nop 0
	v_fmac_f32_dpp v11, v4, v32 row_shr:2 row_mask:0xf bank_mask:0xf
	v_fmac_f32_dpp v10, v5, v33 row_shr:2 row_mask:0xf bank_mask:0xf
	s_nop 0
	v_fmac_f32_dpp v11, v0, v32 row_shl:14 row_mask:0xf bank_mask:0xf
	v_fmac_f32_dpp v10, v1, v33 row_shl:14 row_mask:0xf bank_mask:0xf
	s_nop 0
	v_fma_f32 v5, v42, v6, v46
	v_fma_f32 v4, v43, v7, v47
	s_nop 0
	v_fmac_f32_dpp v5, v6, v38 row_shr:1 row_mask:0xf bank_mask:0xf
	v_fmac_f32_dpp v4, v7, v39 row_shr:1 row_mask:0xf bank_mask:0xf
	s_nop 0
	v_fmac_f32_dpp v5, v2, v38 row_shl:15 row_mask:0xf bank_mask:0xf
	v_fmac_f32_dpp v4, v3, v39 row_shl:15 row_mask:0xf bank_mask:0xf
	s_nop 0
	v_fmac_f32_dpp v5, v6, v34 row_shr:2 row_mask:0xf bank_mask:0xf
	v_fmac_f32_dpp v4, v7, v35 row_shr:2 row_mask:0xf bank_mask:0xf
	s_nop 0
	v_fmac_f32_dpp v5, v2, v34 row_shl:14 row_mask:0xf bank_mask:0xf
	v_fmac_f32_dpp v4, v3, v35 row_shl:14 row_mask:0xf bank_mask:0xf
	s_waitcnt lgkmcnt(0)
	v_fma_f32 v18, v40, v0, v44
	v_fma_f32 v7, v41, v1, v45
	v_fma_f32 v6, v42, v2, v46
	v_fmac_f32_dpp v18, v0, v36 row_shr:1 row_mask:0xf bank_mask:0xf
	v_fmac_f32_dpp v7, v1, v37 row_shr:1 row_mask:0xf bank_mask:0xf
	v_fmac_f32_dpp v6, v2, v38 row_shr:1 row_mask:0xf bank_mask:0xf
	v_fmac_f32_dpp v18, v48, v36 row_shl:15 row_mask:0xf bank_mask:0xf
	v_fmac_f32_dpp v7, v49, v37 row_shl:15 row_mask:0xf bank_mask:0xf
	v_fmac_f32_dpp v6, v50, v38 row_shl:15 row_mask:0xf bank_mask:0xf
	v_fmac_f32_dpp v18, v0, v32 row_shr:2 row_mask:0xf bank_mask:0xf
	v_fmac_f32_dpp v7, v1, v33 row_shr:2 row_mask:0xf bank_mask:0xf
	v_fmac_f32_dpp v6, v2, v34 row_shr:2 row_mask:0xf bank_mask:0xf
	v_fmac_f32_dpp v18, v48, v32 row_shl:14 row_mask:0xf bank_mask:0xf
	v_fmac_f32_dpp v7, v49, v33 row_shl:14 row_mask:0xf bank_mask:0xf
	v_fmac_f32_dpp v6, v50, v34 row_shl:14 row_mask:0xf bank_mask:0xf
	s_nop 0
	s_nop 0
	v_fma_f32 v2, v43, v3, v47
	s_nop 1
	v_fmac_f32_dpp v2, v3, v39 row_shr:1 row_mask:0xf bank_mask:0xf
	s_nop 1
	v_fmac_f32_dpp v2, v51, v39 row_shl:15 row_mask:0xf bank_mask:0xf
	s_nop 1
	v_fmac_f32_dpp v2, v3, v35 row_shr:2 row_mask:0xf bank_mask:0xf
	s_nop 1
	v_fmac_f32_dpp v2, v51, v35 row_shl:14 row_mask:0xf bank_mask:0xf
	s_and_saveexec_b64 s[8:9], s[66:67]
	s_cbranch_execz .LBB0_734
	v_lshl_or_b32 v3, s88, 1, v153
	v_mov_b64_e32 v[0:1], s[54:55]
	v_ashrrev_i32_e32 v151, 31, v150
	v_mad_i64_i32 v[0:1], s[0:1], v3, s20, v[0:1]
	v_lshl_add_u64 v[0:1], v[150:151], 2, v[0:1]
	s_mov_b64 s[0:1], 0x5800
	global_store_dwordx4 v[0:1], v[88:91], off
	global_store_dwordx4 v[0:1], v[84:87], off offset:16
	v_lshl_add_u64 v[32:33], v[0:1], 0, s[0:1]
	v_add_co_u32_e32 v0, vcc, 0x5000, v0
	s_nop 1
	v_addc_co_u32_e32 v1, vcc, 0, v1, vcc
	global_store_dwordx4 v[0:1], v[52:55], off offset:2048
	global_store_dwordx4 v[32:33], v[20:23], off offset:16
	s_branch .LBB0_734
